# conv unit: tap-weight loads issued ahead of the staging waits and the barrier moved behind them
# baseline (speedup 1.0000x reference)
.LBB0_997:
	s_or_b64 exec, exec, s[10:11]
	v_mov_b32_e32 v0, 2
	v_lshlrev_b32_sdwa v152, v0, v8 dst_sel:DWORD dst_unused:UNUSED_PAD src0_sel:DWORD src1_sel:BYTE_0
	v_lshl_add_u64 v[28:29], s[0:1], 0, v[152:153]
	v_add_co_u32_e32 v12, vcc, 0x1000, v28
	s_movk_i32 s10, 0x2000
	s_nop 0
	v_addc_co_u32_e32 v13, vcc, 0, v29, vcc
	global_load_dword v3, v152, s[0:1]
	global_load_dword v2, v152, s[0:1] offset:1024
	global_load_dword v1, v152, s[0:1] offset:2048
	global_load_dword v0, v152, s[0:1] offset:3072
	global_load_dword v7, v[12:13], off
	global_load_dword v6, v[12:13], off offset:1024
	global_load_dword v5, v[12:13], off offset:2048
	global_load_dword v4, v[12:13], off offset:3072
	v_add_co_u32_e32 v12, vcc, s10, v28
	s_movk_i32 s10, 0x3000
	s_nop 0
	v_addc_co_u32_e32 v13, vcc, 0, v29, vcc
	v_add_co_u32_e32 v20, vcc, s10, v28
	s_movk_i32 s10, 0x4000
	s_nop 0
	v_addc_co_u32_e32 v21, vcc, 0, v29, vcc
	v_add_co_u32_e32 v24, vcc, s10, v28
	s_movk_i32 s10, 0x5000
	s_nop 0
	v_addc_co_u32_e32 v25, vcc, 0, v29, vcc
	v_add_co_u32_e32 v30, vcc, s10, v28
	s_movk_i32 s10, 0x6000
	s_nop 0
	v_addc_co_u32_e32 v31, vcc, 0, v29, vcc
	v_add_co_u32_e32 v32, vcc, s10, v28
	s_movk_i32 s10, 0x7000
	s_nop 0
	v_addc_co_u32_e32 v33, vcc, 0, v29, vcc
	v_add_co_u32_e32 v36, vcc, s10, v28
	global_load_dword v18, v[20:21], off offset:-4096
	global_load_dword v17, v[12:13], off offset:1024
	global_load_dword v16, v[12:13], off offset:2048
	global_load_dword v15, v[12:13], off offset:3072
	global_load_dword v14, v[20:21], off
	s_nop 0
	global_load_dword v13, v[20:21], off offset:1024
	global_load_dword v12, v[20:21], off offset:2048
	global_load_dword v9, v[20:21], off offset:3072
	v_addc_co_u32_e32 v37, vcc, 0, v29, vcc
	global_load_dword v19, v[30:31], off offset:-4096
	global_load_dword v22, v[24:25], off offset:1024
	global_load_dword v21, v[24:25], off offset:2048
	global_load_dword v20, v[24:25], off offset:3072
	global_load_dword v26, v[30:31], off
	s_nop 0
	global_load_dword v25, v[30:31], off offset:1024
	global_load_dword v24, v[30:31], off offset:2048
	global_load_dword v23, v[30:31], off offset:3072
	global_load_dword v28, v[36:37], off offset:-4096
	s_nop 0
	global_load_dword v31, v[32:33], off offset:1024
	global_load_dword v30, v[32:33], off offset:2048
	global_load_dword v29, v[32:33], off offset:3072
	global_load_dword v34, v[36:37], off
	s_nop 0
	global_load_dword v33, v[36:37], off offset:1024
	global_load_dword v32, v[36:37], off offset:2048
	s_waitcnt vmcnt(36)
	ds_write_b128 v124, v[92:95]
	s_waitcnt vmcnt(35)
	ds_write_b128 v124, v[96:99] offset:8192
	s_waitcnt vmcnt(34)
	ds_write_b128 v124, v[100:103] offset:16384
	s_waitcnt vmcnt(33)
	ds_write_b128 v124, v[104:107] offset:24576
	s_waitcnt vmcnt(32)
	ds_write_b128 v124, v[108:111] offset:32768
	s_waitcnt vmcnt(31)
	s_and_saveexec_b64 s[14:15], s[12:13]
	ds_write_b128 v124, v[112:115] offset:40960
	s_or_b64 exec, exec, s[14:15]
	s_waitcnt lgkmcnt(0)
	s_barrier
	v_ashrrev_i32_e32 v27, 3, v8
	v_lshlrev_b32_sdwa v36, v229, v8 dst_sel:DWORD dst_unused:UNUSED_PAD src0_sel:DWORD src1_sel:BYTE_0
	v_and_b32_e32 v61, 0xffffffe0, v27
	v_add_u32_e32 v62, 0, v36
	v_lshl_add_u32 v78, v61, 9, v62
	v_or_b32_e32 v43, 1, v61
	ds_read_u16 v37, v78
	v_lshl_add_u32 v35, v43, 9, v62
	ds_read_u16 v38, v35
	v_or_b32_e32 v48, 3, v61
	v_or_b32_e32 v72, 6, v61
	v_or_b32_e32 v44, 2, v61
	s_waitcnt lgkmcnt(1)
	v_lshlrev_b32_e32 v45, 16, v37
	v_lshl_add_u32 v37, v48, 9, v62
	v_or_b32_e32 v49, 4, v61
	v_lshl_add_u32 v40, v72, 9, v62
	v_or_b32_e32 v73, 7, v61
	ds_read_u16 v37, v37
	ds_read_u16 v40, v40
	v_lshl_add_u32 v35, v44, 9, v62
	s_waitcnt lgkmcnt(2)
	v_lshlrev_b32_e32 v46, 16, v38
	v_lshl_add_u32 v38, v49, 9, v62
	v_lshl_add_u32 v41, v73, 9, v62
	ds_read_u16 v39, v35
	ds_read_u16 v38, v38
	ds_read_u16 v41, v41
	global_load_dword v35, v152, s[2:3]
	v_or_b32_e32 v50, 5, v61
	s_waitcnt lgkmcnt(2)
	v_lshlrev_b32_e32 v47, 16, v39
	v_lshl_add_u32 v39, v50, 9, v62
	ds_read_u16 v39, v39
	v_or_b32_e32 v60, 8, v61
	v_lshlrev_b32_e32 v74, 16, v37
	v_lshl_add_u32 v37, v60, 9, v62
	s_waitcnt lgkmcnt(2)
	v_lshlrev_b32_e32 v75, 16, v38
	s_waitcnt lgkmcnt(0)
	v_lshlrev_b32_e32 v76, 16, v39
	v_lshlrev_b32_e32 v77, 16, v40
	v_lshlrev_b32_e32 v79, 16, v41
	ds_read_u16 v37, v37
	ds_read_u16 v38, v78 offset:4608
	ds_read_u16 v39, v78 offset:5120
	ds_read_u16 v40, v78 offset:5632
	ds_read_u16 v41, v78 offset:6144
	v_or_b32_e32 v70, 16, v61
	s_waitcnt lgkmcnt(4)
	v_lshlrev_b32_e32 v80, 16, v37
	s_waitcnt lgkmcnt(3)
	v_lshlrev_b32_e32 v81, 16, v38
	s_waitcnt lgkmcnt(1)
	v_lshlrev_b32_e32 v83, 16, v40
	v_lshl_add_u32 v40, v70, 9, v62
	v_lshlrev_b32_e32 v82, 16, v39
	s_waitcnt lgkmcnt(0)
	v_lshlrev_b32_e32 v84, 16, v41
	ds_read_u16 v37, v78 offset:6656
	ds_read_u16 v38, v78 offset:7168
	ds_read_u16 v39, v78 offset:7680
	ds_read_u16 v40, v40
	ds_read_u16 v41, v78 offset:8704
	v_or_b32_e32 v51, 24, v61
	s_waitcnt lgkmcnt(4)
	v_lshlrev_b32_e32 v85, 16, v37
	s_waitcnt lgkmcnt(3)
	v_lshlrev_b32_e32 v86, 16, v38
	s_waitcnt lgkmcnt(2)
	v_lshlrev_b32_e32 v87, 16, v39
	s_waitcnt lgkmcnt(1)
	v_lshlrev_b32_e32 v71, 16, v40
	s_waitcnt lgkmcnt(0)
	v_lshlrev_b32_e32 v53, 16, v41
	ds_read_u16 v37, v78 offset:9216
	ds_read_u16 v38, v78 offset:9728
	ds_read_u16 v39, v78 offset:10240
	ds_read_u16 v40, v78 offset:10752
	ds_read_u16 v41, v78 offset:11264
	s_waitcnt lgkmcnt(4)
	v_lshlrev_b32_e32 v54, 16, v37
	s_waitcnt lgkmcnt(3)
	v_lshlrev_b32_e32 v55, 16, v38
	v_lshl_add_u32 v38, v51, 9, v62
	s_waitcnt lgkmcnt(2)
	v_lshlrev_b32_e32 v56, 16, v39
	s_waitcnt lgkmcnt(1)
	v_lshlrev_b32_e32 v57, 16, v40
	s_waitcnt lgkmcnt(0)
	v_lshlrev_b32_e32 v58, 16, v41
	ds_read_u16 v37, v78 offset:11776
	ds_read_u16 v38, v38
	ds_read_u16 v39, v78 offset:12800
	ds_read_u16 v40, v78 offset:13312
	ds_read_u16 v41, v78 offset:13824
	v_add_u32_e32 v36, v62, v36
	s_waitcnt lgkmcnt(3)
	v_lshlrev_b32_e32 v52, 16, v38
	s_waitcnt lgkmcnt(2)
	v_lshlrev_b32_e32 v63, 16, v39
	s_waitcnt lgkmcnt(1)
	v_lshlrev_b32_e32 v64, 16, v40
	v_mov_b32_e32 v40, 0x3e00
	v_lshl_or_b32 v40, v27, 9, v40
	v_lshlrev_b32_e32 v59, 16, v37
	ds_read_u16 v37, v78 offset:14336
	ds_read_u16 v38, v78 offset:14848
	ds_read_u16 v39, v78 offset:15360
	v_add_u32_e32 v40, v62, v40
	s_waitcnt lgkmcnt(3)
	v_lshlrev_b32_e32 v65, 16, v41
	ds_read_u16 v40, v40
	ds_read_u16 v41, v78 offset:16384
	s_waitcnt lgkmcnt(3)
	v_lshlrev_b32_e32 v67, 16, v38
	s_waitcnt lgkmcnt(2)
	v_lshlrev_b32_e32 v68, 16, v39
	v_lshlrev_b32_e32 v66, 16, v37
	s_waitcnt lgkmcnt(1)
	v_lshlrev_b32_e32 v69, 16, v40
	ds_read_u16 v38, v78 offset:16896
	ds_read_u16 v39, v78 offset:17408
	ds_read_u16 v40, v78 offset:17920
	ds_read_u16 v88, v78 offset:18432
	ds_read_u16 v89, v78 offset:18944
	s_waitcnt lgkmcnt(5)
	v_lshlrev_b32_e32 v37, 16, v41
	s_waitcnt lgkmcnt(3)
	v_lshlrev_b32_e32 v41, 16, v39
	v_lshl_add_u32 v43, v43, 10, v36
	s_waitcnt lgkmcnt(1)
	v_lshlrev_b32_e32 v39, 16, v88
	v_lshl_add_u32 v88, v61, 10, v36
	v_lshl_add_u32 v44, v44, 10, v36
	v_lshlrev_b32_e32 v42, 16, v38
	v_lshlrev_b32_e32 v40, 16, v40
	s_waitcnt lgkmcnt(0)
	v_lshlrev_b32_e32 v38, 16, v89
	v_lshl_add_u32 v60, v60, 10, v36
	v_lshl_add_u32 v70, v70, 10, v36
	v_lshl_add_u32 v51, v51, 10, v36
	s_add_u32 s8, s19, s8
	s_addc_u32 s9, 0, s9
	s_mov_b32 s10, 0
	s_waitcnt vmcnt(0)
	v_fma_f32 v45, v3, v45, v35
	v_fmac_f32_e32 v45, v2, v46
	v_fmac_f32_e32 v45, v1, v47
	v_fmac_f32_e32 v45, v0, v74
	v_fmac_f32_e32 v45, v7, v75
	v_fmac_f32_e32 v45, v6, v76
	v_fmac_f32_e32 v45, v5, v77
	v_fmac_f32_e32 v45, v4, v79
	v_fmac_f32_e32 v45, v18, v80
	v_fmac_f32_e32 v45, v17, v81
	v_fmac_f32_e32 v45, v16, v82
	v_fmac_f32_e32 v45, v15, v83
	v_fmac_f32_e32 v45, v14, v84
	v_fmac_f32_e32 v45, v13, v85
	v_fmac_f32_e32 v45, v12, v86
	v_fmac_f32_e32 v45, v9, v87
	v_fmac_f32_e32 v45, v19, v71
	v_fmac_f32_e32 v45, v22, v53
	v_fmac_f32_e32 v45, v21, v54
	v_fmac_f32_e32 v45, v20, v55
	v_fmac_f32_e32 v45, v26, v56
	v_fmac_f32_e32 v45, v25, v57
	v_fmac_f32_e32 v45, v24, v58
	v_fmac_f32_e32 v45, v23, v59
	v_fmac_f32_e32 v45, v28, v52
	v_fmac_f32_e32 v45, v31, v63
	v_fmac_f32_e32 v45, v30, v64
	v_fmac_f32_e32 v45, v29, v65
	v_fmac_f32_e32 v45, v34, v66
	v_fmac_f32_e32 v45, v33, v67
	v_fmac_f32_e32 v45, v32, v68
	ds_write_b32 v88, v45 offset:49152
	v_fma_f32 v45, v3, v46, v35
	v_fmac_f32_e32 v45, v2, v47
	v_fmac_f32_e32 v45, v1, v74
	v_fmac_f32_e32 v45, v0, v75
	v_fmac_f32_e32 v45, v7, v76
	v_fmac_f32_e32 v45, v6, v77
	v_fmac_f32_e32 v45, v5, v79
	v_fmac_f32_e32 v45, v4, v80
	v_fmac_f32_e32 v45, v18, v81
	v_fmac_f32_e32 v45, v17, v82
	v_fmac_f32_e32 v45, v16, v83
	v_fmac_f32_e32 v45, v15, v84
	v_fmac_f32_e32 v45, v14, v85
	v_fmac_f32_e32 v45, v13, v86
	v_fmac_f32_e32 v45, v12, v87
	v_fmac_f32_e32 v45, v9, v71
	v_fmac_f32_e32 v45, v19, v53
	v_fmac_f32_e32 v45, v22, v54
	v_fmac_f32_e32 v45, v21, v55
	v_fmac_f32_e32 v45, v20, v56
	v_fmac_f32_e32 v45, v26, v57
	v_fmac_f32_e32 v45, v25, v58
	v_fmac_f32_e32 v45, v24, v59
	v_fmac_f32_e32 v45, v23, v52
	v_fmac_f32_e32 v45, v28, v63
	v_fmac_f32_e32 v45, v31, v64
	v_fmac_f32_e32 v45, v30, v65
	v_fmac_f32_e32 v45, v29, v66
	v_fmac_f32_e32 v45, v34, v67
	v_fmac_f32_e32 v45, v33, v68
	v_fmac_f32_e32 v45, v32, v69
	ds_write_b32 v43, v45 offset:49152
	v_fma_f32 v43, v3, v47, v35
	v_fmac_f32_e32 v43, v2, v74
	v_fmac_f32_e32 v43, v1, v75
	v_fmac_f32_e32 v43, v0, v76
	v_fmac_f32_e32 v43, v7, v77
	v_fmac_f32_e32 v43, v6, v79
	v_fmac_f32_e32 v43, v5, v80
	v_fmac_f32_e32 v43, v4, v81
	v_fmac_f32_e32 v43, v18, v82
	v_fmac_f32_e32 v43, v17, v83
	v_fmac_f32_e32 v43, v16, v84
	v_fmac_f32_e32 v43, v15, v85
	v_fmac_f32_e32 v43, v14, v86
	v_fmac_f32_e32 v43, v13, v87
	v_fmac_f32_e32 v43, v12, v71
	v_fmac_f32_e32 v43, v9, v53
	v_fmac_f32_e32 v43, v19, v54
	v_fmac_f32_e32 v43, v22, v55
	v_fmac_f32_e32 v43, v21, v56
	v_fmac_f32_e32 v43, v20, v57
	v_fmac_f32_e32 v43, v26, v58
	v_fmac_f32_e32 v43, v25, v59
	v_fmac_f32_e32 v43, v24, v52
	v_fmac_f32_e32 v43, v23, v63
	v_fmac_f32_e32 v43, v28, v64
	v_fmac_f32_e32 v43, v31, v65
	v_fmac_f32_e32 v43, v30, v66
	v_fmac_f32_e32 v43, v29, v67
	v_fmac_f32_e32 v43, v34, v68
	v_fmac_f32_e32 v43, v33, v69
	v_fmac_f32_e32 v43, v32, v37
	ds_write_b32 v44, v43 offset:49152
	v_fma_f32 v43, v3, v74, v35
	v_fmac_f32_e32 v43, v2, v75
	v_fmac_f32_e32 v43, v1, v76
	v_fmac_f32_e32 v43, v0, v77
	v_fmac_f32_e32 v43, v7, v79
	v_fmac_f32_e32 v43, v6, v80
	v_fmac_f32_e32 v43, v5, v81
	v_fmac_f32_e32 v43, v4, v82
	v_fmac_f32_e32 v43, v18, v83
	v_fmac_f32_e32 v43, v17, v84
	v_fmac_f32_e32 v43, v16, v85
	v_fmac_f32_e32 v43, v15, v86
	v_fmac_f32_e32 v43, v14, v87
	v_fmac_f32_e32 v43, v13, v71
	v_fmac_f32_e32 v43, v12, v53
	v_fmac_f32_e32 v43, v9, v54
	v_fmac_f32_e32 v43, v19, v55
	v_fmac_f32_e32 v43, v22, v56
	v_fmac_f32_e32 v43, v21, v57
	v_fmac_f32_e32 v43, v20, v58
	v_fmac_f32_e32 v43, v26, v59
	v_fmac_f32_e32 v43, v25, v52
	v_fmac_f32_e32 v43, v24, v63
	v_fmac_f32_e32 v43, v23, v64
	v_fmac_f32_e32 v43, v28, v65
	v_fmac_f32_e32 v43, v31, v66
	v_fmac_f32_e32 v43, v30, v67
	v_fmac_f32_e32 v43, v29, v68
	v_fmac_f32_e32 v43, v34, v69
	v_fmac_f32_e32 v43, v33, v37
	v_fmac_f32_e32 v43, v32, v42
	v_lshl_add_u32 v44, v48, 10, v36
	ds_write_b32 v44, v43 offset:49152
	v_fma_f32 v43, v3, v75, v35
	v_fmac_f32_e32 v43, v2, v76
	v_fmac_f32_e32 v43, v1, v77
	v_fmac_f32_e32 v43, v0, v79
	v_fmac_f32_e32 v43, v7, v80
	v_fmac_f32_e32 v43, v6, v81
	v_fmac_f32_e32 v43, v5, v82
	v_fmac_f32_e32 v43, v4, v83
	v_fmac_f32_e32 v43, v18, v84
	v_fmac_f32_e32 v43, v17, v85
	v_fmac_f32_e32 v43, v16, v86
	v_fmac_f32_e32 v43, v15, v87
	v_fmac_f32_e32 v43, v14, v71
	v_fmac_f32_e32 v43, v13, v53
	v_fmac_f32_e32 v43, v12, v54
	v_fmac_f32_e32 v43, v9, v55
	v_fmac_f32_e32 v43, v19, v56
	v_fmac_f32_e32 v43, v22, v57
	v_fmac_f32_e32 v43, v21, v58
	v_fmac_f32_e32 v43, v20, v59
	v_fmac_f32_e32 v43, v26, v52
	v_fmac_f32_e32 v43, v25, v63
	v_fmac_f32_e32 v43, v24, v64
	v_fmac_f32_e32 v43, v23, v65
	v_fmac_f32_e32 v43, v28, v66
	v_fmac_f32_e32 v43, v31, v67
	v_fmac_f32_e32 v43, v30, v68
	v_fmac_f32_e32 v43, v29, v69
	v_fmac_f32_e32 v43, v34, v37
	v_fmac_f32_e32 v43, v33, v42
	v_fmac_f32_e32 v43, v32, v41
	v_lshl_add_u32 v44, v49, 10, v36
	ds_write_b32 v44, v43 offset:49152
	v_fma_f32 v43, v3, v76, v35
	v_fmac_f32_e32 v43, v2, v77
	v_fmac_f32_e32 v43, v1, v79
	v_fmac_f32_e32 v43, v0, v80
	v_fmac_f32_e32 v43, v7, v81
	v_fmac_f32_e32 v43, v6, v82
	v_fmac_f32_e32 v43, v5, v83
	v_fmac_f32_e32 v43, v4, v84
	v_fmac_f32_e32 v43, v18, v85
	v_fmac_f32_e32 v43, v17, v86
	v_fmac_f32_e32 v43, v16, v87
	v_fmac_f32_e32 v43, v15, v71
	v_fmac_f32_e32 v43, v14, v53
	v_fmac_f32_e32 v43, v13, v54
	v_fmac_f32_e32 v43, v12, v55
	v_fmac_f32_e32 v43, v9, v56
	v_fmac_f32_e32 v43, v19, v57
	v_fmac_f32_e32 v43, v22, v58
	v_fmac_f32_e32 v43, v21, v59
	v_fmac_f32_e32 v43, v20, v52
	v_fmac_f32_e32 v43, v26, v63
	v_fmac_f32_e32 v43, v25, v64
	v_fmac_f32_e32 v43, v24, v65
	v_fmac_f32_e32 v43, v23, v66
	v_fmac_f32_e32 v43, v28, v67
	v_fmac_f32_e32 v43, v31, v68
	v_fmac_f32_e32 v43, v30, v69
	v_fmac_f32_e32 v43, v29, v37
	v_fmac_f32_e32 v43, v34, v42
	v_fmac_f32_e32 v43, v33, v41
	v_fmac_f32_e32 v43, v32, v40
	v_lshl_add_u32 v44, v50, 10, v36
	ds_write_b32 v44, v43 offset:49152
	v_fma_f32 v43, v3, v77, v35
	v_fmac_f32_e32 v43, v2, v79
	v_fmac_f32_e32 v43, v1, v80
	v_fmac_f32_e32 v43, v0, v81
	v_fmac_f32_e32 v43, v7, v82
	v_fmac_f32_e32 v43, v6, v83
	v_fmac_f32_e32 v43, v5, v84
	v_fmac_f32_e32 v43, v4, v85
	v_fmac_f32_e32 v43, v18, v86
	v_fmac_f32_e32 v43, v17, v87
	v_fmac_f32_e32 v43, v16, v71
	v_fmac_f32_e32 v43, v15, v53
	v_fmac_f32_e32 v43, v14, v54
	v_fmac_f32_e32 v43, v13, v55
	v_fmac_f32_e32 v43, v12, v56
	v_fmac_f32_e32 v43, v9, v57
	v_fmac_f32_e32 v43, v19, v58
	v_fmac_f32_e32 v43, v22, v59
	v_fmac_f32_e32 v43, v21, v52
	v_fmac_f32_e32 v43, v20, v63
	v_fmac_f32_e32 v43, v26, v64
	v_fmac_f32_e32 v43, v25, v65
	v_fmac_f32_e32 v43, v24, v66
	v_fmac_f32_e32 v43, v23, v67
	v_fmac_f32_e32 v43, v28, v68
	v_fmac_f32_e32 v43, v31, v69
	v_fmac_f32_e32 v43, v30, v37
	v_fmac_f32_e32 v43, v29, v42
	v_fmac_f32_e32 v43, v34, v41
	v_fmac_f32_e32 v43, v33, v40
	v_fmac_f32_e32 v43, v32, v39
	v_lshl_add_u32 v44, v72, 10, v36
	ds_write_b32 v44, v43 offset:49152
	v_fma_f32 v43, v3, v79, v35
	v_fmac_f32_e32 v43, v2, v80
	v_fmac_f32_e32 v43, v1, v81
	v_fmac_f32_e32 v43, v0, v82
	v_fmac_f32_e32 v43, v7, v83
	v_fmac_f32_e32 v43, v6, v84
	v_fmac_f32_e32 v43, v5, v85
	v_fmac_f32_e32 v43, v4, v86
	v_fmac_f32_e32 v43, v18, v87
	v_fmac_f32_e32 v43, v17, v71
	v_fmac_f32_e32 v43, v16, v53
	v_fmac_f32_e32 v43, v15, v54
	v_fmac_f32_e32 v43, v14, v55
	v_fmac_f32_e32 v43, v13, v56
	v_fmac_f32_e32 v43, v12, v57
	v_fmac_f32_e32 v43, v9, v58
	v_fmac_f32_e32 v43, v19, v59
	v_fmac_f32_e32 v43, v22, v52
	v_fmac_f32_e32 v43, v21, v63
	v_fmac_f32_e32 v43, v20, v64
	v_fmac_f32_e32 v43, v26, v65
	v_fmac_f32_e32 v43, v25, v66
	v_fmac_f32_e32 v43, v24, v67
	v_fmac_f32_e32 v43, v23, v68
	v_fmac_f32_e32 v43, v28, v69
	v_fmac_f32_e32 v43, v31, v37
	v_or_b32_e32 v74, 9, v61
	v_fmac_f32_e32 v43, v30, v42
	v_lshl_add_u32 v44, v74, 9, v62
	v_or_b32_e32 v75, 10, v61
	v_fmac_f32_e32 v43, v29, v41
	ds_read_u16 v44, v44
	v_lshl_add_u32 v45, v75, 9, v62
	v_fmac_f32_e32 v43, v34, v40
	ds_read_u16 v45, v45
	v_fmac_f32_e32 v43, v33, v39
	v_fmac_f32_e32 v43, v32, v38
	v_lshl_add_u32 v46, v73, 10, v36
	v_or_b32_e32 v77, 11, v61
	v_or_b32_e32 v82, 14, v61
	ds_write_b32 v46, v43 offset:49152
	v_lshl_add_u32 v43, v77, 9, v62
	v_or_b32_e32 v79, 12, v61
	v_lshl_add_u32 v46, v82, 9, v62
	v_or_b32_e32 v81, 13, v61
	ds_read_u16 v46, v46
	ds_read_u16 v43, v43
	s_waitcnt lgkmcnt(4)
	v_lshlrev_b32_e32 v73, 16, v44
	v_lshl_add_u32 v44, v79, 9, v62
	s_waitcnt lgkmcnt(3)
	v_lshlrev_b32_e32 v76, 16, v45
	ds_read_u16 v44, v44
	v_lshl_add_u32 v45, v81, 9, v62
	ds_read_u16 v45, v45
	v_or_b32_e32 v83, 15, v61
	v_lshl_add_u32 v47, v83, 9, v62
	v_fma_f32 v80, v3, v80, v35
	ds_read_u16 v47, v47
	v_fmac_f32_e32 v80, v2, v73
	s_waitcnt lgkmcnt(3)
	v_lshlrev_b32_e32 v84, 16, v43
	v_fmac_f32_e32 v80, v1, v76
	s_waitcnt lgkmcnt(2)
	v_lshlrev_b32_e32 v85, 16, v44
	v_fmac_f32_e32 v80, v0, v84
	s_waitcnt lgkmcnt(1)
	v_lshlrev_b32_e32 v86, 16, v45
	v_fmac_f32_e32 v80, v7, v85
	v_lshlrev_b32_e32 v87, 16, v46
	v_fmac_f32_e32 v80, v6, v86
	s_waitcnt lgkmcnt(0)
	v_lshlrev_b32_e32 v88, 16, v47
	ds_read_u16 v43, v78 offset:8192
	ds_read_u16 v44, v78 offset:12288
	ds_read_u16 v45, v78 offset:19456
	ds_read_u16 v46, v78 offset:19968
	ds_read_u16 v48, v78 offset:20480
	v_fmac_f32_e32 v80, v5, v87
	s_waitcnt lgkmcnt(4)
	v_lshlrev_b32_e32 v89, 16, v43
	v_fmac_f32_e32 v80, v4, v88
	v_fmac_f32_e32 v80, v18, v89
	v_fmac_f32_e32 v80, v17, v53
	v_fmac_f32_e32 v80, v16, v54
	v_fmac_f32_e32 v80, v15, v55
	v_fmac_f32_e32 v80, v14, v56
	v_fmac_f32_e32 v80, v13, v57
	v_fmac_f32_e32 v80, v12, v58
	s_waitcnt lgkmcnt(3)
	v_lshlrev_b32_e32 v72, 16, v44
	v_fmac_f32_e32 v80, v9, v59
	v_fmac_f32_e32 v80, v19, v72
	v_fmac_f32_e32 v80, v22, v63
	v_fmac_f32_e32 v80, v21, v64
	v_fmac_f32_e32 v80, v20, v65
	v_fmac_f32_e32 v80, v26, v66
	v_fmac_f32_e32 v80, v25, v67
	v_fmac_f32_e32 v80, v24, v68
	v_fmac_f32_e32 v80, v23, v69
	v_fmac_f32_e32 v80, v28, v37
	v_fmac_f32_e32 v80, v31, v42
	v_fmac_f32_e32 v80, v30, v41
	v_fmac_f32_e32 v80, v29, v40
	v_fmac_f32_e32 v80, v34, v39
	s_waitcnt lgkmcnt(2)
	v_lshlrev_b32_e32 v47, 16, v45
	v_fmac_f32_e32 v80, v33, v38
	v_fmac_f32_e32 v80, v32, v47
	s_waitcnt lgkmcnt(1)
	v_lshlrev_b32_e32 v45, 16, v46
	s_waitcnt lgkmcnt(0)
	v_lshlrev_b32_e32 v43, 16, v48
	ds_read_u16 v44, v78 offset:20992
	ds_read_u16 v46, v78 offset:21504
	ds_read_u16 v48, v78 offset:22016
	ds_read_u16 v90, v78 offset:22528
	ds_read_u16 v91, v78 offset:23040
	ds_write_b32 v60, v80 offset:49152
	v_fma_f32 v60, v3, v73, v35
	v_fmac_f32_e32 v60, v2, v76
	v_fmac_f32_e32 v60, v1, v84
	v_fmac_f32_e32 v60, v0, v85
	v_fmac_f32_e32 v60, v7, v86
	v_fmac_f32_e32 v60, v6, v87
	v_fmac_f32_e32 v60, v5, v88
	v_fmac_f32_e32 v60, v4, v89
	v_fmac_f32_e32 v60, v18, v53
	v_fmac_f32_e32 v60, v17, v54
	v_fmac_f32_e32 v60, v16, v55
	v_fmac_f32_e32 v60, v15, v56
	v_fmac_f32_e32 v60, v14, v57
	v_fmac_f32_e32 v60, v13, v58
	v_fmac_f32_e32 v60, v12, v59
	v_fmac_f32_e32 v60, v9, v72
	v_fmac_f32_e32 v60, v19, v63
	v_fmac_f32_e32 v60, v22, v64
	v_fmac_f32_e32 v60, v21, v65
	v_fmac_f32_e32 v60, v20, v66
	v_fmac_f32_e32 v60, v26, v67
	v_fmac_f32_e32 v60, v25, v68
	v_fmac_f32_e32 v60, v24, v69
	v_fmac_f32_e32 v60, v23, v37
	v_fmac_f32_e32 v60, v28, v42
	v_fmac_f32_e32 v60, v31, v41
	v_fmac_f32_e32 v60, v30, v40
	v_fmac_f32_e32 v60, v29, v39
	v_fmac_f32_e32 v60, v34, v38
	v_fmac_f32_e32 v60, v33, v47
	v_fmac_f32_e32 v60, v32, v45
	v_lshl_add_u32 v73, v74, 10, v36
	ds_write_b32 v73, v60 offset:49152
	v_fma_f32 v60, v3, v76, v35
	v_fmac_f32_e32 v60, v2, v84
	v_fmac_f32_e32 v60, v1, v85
	v_fmac_f32_e32 v60, v0, v86
	v_fmac_f32_e32 v60, v7, v87
	v_fmac_f32_e32 v60, v6, v88
	v_fmac_f32_e32 v60, v5, v89
	v_fmac_f32_e32 v60, v4, v53
	v_fmac_f32_e32 v60, v18, v54
	v_fmac_f32_e32 v60, v17, v55
	v_fmac_f32_e32 v60, v16, v56
	v_fmac_f32_e32 v60, v15, v57
	v_fmac_f32_e32 v60, v14, v58
	v_fmac_f32_e32 v60, v13, v59
	v_fmac_f32_e32 v60, v12, v72
	v_fmac_f32_e32 v60, v9, v63
	v_fmac_f32_e32 v60, v19, v64
	v_fmac_f32_e32 v60, v22, v65
	v_fmac_f32_e32 v60, v21, v66
	v_fmac_f32_e32 v60, v20, v67
	v_fmac_f32_e32 v60, v26, v68
	v_fmac_f32_e32 v60, v25, v69
	v_fmac_f32_e32 v60, v24, v37
	v_fmac_f32_e32 v60, v23, v42
	v_fmac_f32_e32 v60, v28, v41
	v_fmac_f32_e32 v60, v31, v40
	v_fmac_f32_e32 v60, v30, v39
	v_fmac_f32_e32 v60, v29, v38
	v_fmac_f32_e32 v60, v34, v47
	v_fmac_f32_e32 v60, v33, v45
	v_fmac_f32_e32 v60, v32, v43
	v_lshl_add_u32 v73, v75, 10, v36
	ds_write_b32 v73, v60 offset:49152
	v_fma_f32 v60, v3, v84, v35
	v_fmac_f32_e32 v60, v2, v85
	v_fmac_f32_e32 v60, v1, v86
	v_fmac_f32_e32 v60, v0, v87
	v_fmac_f32_e32 v60, v7, v88
	v_fmac_f32_e32 v60, v6, v89
	v_fmac_f32_e32 v60, v5, v53
	v_fmac_f32_e32 v60, v4, v54
	v_fmac_f32_e32 v60, v18, v55
	v_fmac_f32_e32 v60, v17, v56
	v_fmac_f32_e32 v60, v16, v57
	v_fmac_f32_e32 v60, v15, v58
	v_fmac_f32_e32 v60, v14, v59
	v_fmac_f32_e32 v60, v13, v72
	v_fmac_f32_e32 v60, v12, v63
	v_fmac_f32_e32 v60, v9, v64
	v_fmac_f32_e32 v60, v19, v65
	v_fmac_f32_e32 v60, v22, v66
	v_fmac_f32_e32 v60, v21, v67
	v_fmac_f32_e32 v60, v20, v68
	v_fmac_f32_e32 v60, v26, v69
	v_fmac_f32_e32 v60, v25, v37
	v_fmac_f32_e32 v60, v24, v42
	v_fmac_f32_e32 v60, v23, v41
	v_fmac_f32_e32 v60, v28, v40
	v_fmac_f32_e32 v60, v31, v39
	v_fmac_f32_e32 v60, v30, v38
	v_fmac_f32_e32 v60, v29, v47
	v_fmac_f32_e32 v60, v34, v45
	s_waitcnt lgkmcnt(7)
	v_lshlrev_b32_e32 v50, 16, v44
	v_fmac_f32_e32 v60, v33, v43
	v_fmac_f32_e32 v60, v32, v50
	v_lshl_add_u32 v73, v77, 10, v36
	ds_write_b32 v73, v60 offset:49152
	v_fma_f32 v60, v3, v85, v35
	v_fmac_f32_e32 v60, v2, v86
	v_fmac_f32_e32 v60, v1, v87
	v_fmac_f32_e32 v60, v0, v88
	v_fmac_f32_e32 v60, v7, v89
	v_fmac_f32_e32 v60, v6, v53
	v_fmac_f32_e32 v60, v5, v54
	v_fmac_f32_e32 v60, v4, v55
	v_fmac_f32_e32 v60, v18, v56
	v_fmac_f32_e32 v60, v17, v57
	v_fmac_f32_e32 v60, v16, v58
	v_fmac_f32_e32 v60, v15, v59
	v_fmac_f32_e32 v60, v14, v72
	v_fmac_f32_e32 v60, v13, v63
	v_fmac_f32_e32 v60, v12, v64
	v_fmac_f32_e32 v60, v9, v65
	v_fmac_f32_e32 v60, v19, v66
	v_fmac_f32_e32 v60, v22, v67
	v_fmac_f32_e32 v60, v21, v68
	v_fmac_f32_e32 v60, v20, v69
	v_fmac_f32_e32 v60, v26, v37
	v_fmac_f32_e32 v60, v25, v42
	v_fmac_f32_e32 v60, v24, v41
	v_fmac_f32_e32 v60, v23, v40
	v_fmac_f32_e32 v60, v28, v39
	v_fmac_f32_e32 v60, v31, v38
	v_fmac_f32_e32 v60, v30, v47
	v_fmac_f32_e32 v60, v29, v45
	v_fmac_f32_e32 v60, v34, v43
	s_waitcnt lgkmcnt(7)
	v_lshlrev_b32_e32 v49, 16, v46
	v_fmac_f32_e32 v60, v33, v50
	v_fmac_f32_e32 v60, v32, v49
	v_lshl_add_u32 v73, v79, 10, v36
	ds_write_b32 v73, v60 offset:49152
	v_fma_f32 v60, v3, v86, v35
	v_fmac_f32_e32 v60, v2, v87
	v_fmac_f32_e32 v60, v1, v88
	v_fmac_f32_e32 v60, v0, v89
	v_fmac_f32_e32 v60, v7, v53
	v_fmac_f32_e32 v60, v6, v54
	v_fmac_f32_e32 v60, v5, v55
	v_fmac_f32_e32 v60, v4, v56
	v_fmac_f32_e32 v60, v18, v57
	v_fmac_f32_e32 v60, v17, v58
	v_fmac_f32_e32 v60, v16, v59
	v_fmac_f32_e32 v60, v15, v72
	v_fmac_f32_e32 v60, v14, v63
	v_fmac_f32_e32 v60, v13, v64
	v_fmac_f32_e32 v60, v12, v65
	v_fmac_f32_e32 v60, v9, v66
	v_fmac_f32_e32 v60, v19, v67
	v_fmac_f32_e32 v60, v22, v68
	v_fmac_f32_e32 v60, v21, v69
	v_fmac_f32_e32 v60, v20, v37
	v_fmac_f32_e32 v60, v26, v42
	v_fmac_f32_e32 v60, v25, v41
	v_fmac_f32_e32 v60, v24, v40
	v_fmac_f32_e32 v60, v23, v39
	v_fmac_f32_e32 v60, v28, v38
	v_fmac_f32_e32 v60, v31, v47
	v_fmac_f32_e32 v60, v30, v45
	v_fmac_f32_e32 v60, v29, v43
	v_fmac_f32_e32 v60, v34, v50
	s_waitcnt lgkmcnt(7)
	v_lshlrev_b32_e32 v48, 16, v48
	v_fmac_f32_e32 v60, v33, v49
	v_fmac_f32_e32 v60, v32, v48
	v_lshl_add_u32 v73, v81, 10, v36
	ds_write_b32 v73, v60 offset:49152
	v_fma_f32 v60, v3, v87, v35
	v_fmac_f32_e32 v60, v2, v88
	v_fmac_f32_e32 v60, v1, v89
	v_fmac_f32_e32 v60, v0, v53
	v_fmac_f32_e32 v60, v7, v54
	v_fmac_f32_e32 v60, v6, v55
	v_fmac_f32_e32 v60, v5, v56
	v_fmac_f32_e32 v60, v4, v57
	v_fmac_f32_e32 v60, v18, v58
	v_fmac_f32_e32 v60, v17, v59
	v_fmac_f32_e32 v60, v16, v72
	v_fmac_f32_e32 v60, v15, v63
	v_fmac_f32_e32 v60, v14, v64
	v_fmac_f32_e32 v60, v13, v65
	v_fmac_f32_e32 v60, v12, v66
	v_fmac_f32_e32 v60, v9, v67
	v_fmac_f32_e32 v60, v19, v68
	v_fmac_f32_e32 v60, v22, v69
	v_fmac_f32_e32 v60, v21, v37
	v_fmac_f32_e32 v60, v20, v42
	v_fmac_f32_e32 v60, v26, v41
	v_fmac_f32_e32 v60, v25, v40
	v_fmac_f32_e32 v60, v24, v39
	v_fmac_f32_e32 v60, v23, v38
	v_fmac_f32_e32 v60, v28, v47
	v_fmac_f32_e32 v60, v31, v45
	v_fmac_f32_e32 v60, v30, v43
	v_fmac_f32_e32 v60, v29, v50
	v_fmac_f32_e32 v60, v34, v49
	s_waitcnt lgkmcnt(7)
	v_lshlrev_b32_e32 v46, 16, v90
	v_fmac_f32_e32 v60, v33, v48
	v_fmac_f32_e32 v60, v32, v46
	v_lshl_add_u32 v73, v82, 10, v36
	ds_write_b32 v73, v60 offset:49152
	v_fma_f32 v60, v3, v88, v35
	v_fmac_f32_e32 v60, v2, v89
	v_fmac_f32_e32 v60, v1, v53
	v_fmac_f32_e32 v60, v0, v54
	v_fmac_f32_e32 v60, v7, v55
	v_fmac_f32_e32 v60, v6, v56
	v_fmac_f32_e32 v60, v5, v57
	v_fmac_f32_e32 v60, v4, v58
	v_fmac_f32_e32 v60, v18, v59
	v_fmac_f32_e32 v60, v17, v72
	v_fmac_f32_e32 v60, v16, v63
	v_fmac_f32_e32 v60, v15, v64
	v_fmac_f32_e32 v60, v14, v65
	v_fmac_f32_e32 v60, v13, v66
	v_fmac_f32_e32 v60, v12, v67
	v_fmac_f32_e32 v60, v9, v68
	v_fmac_f32_e32 v60, v19, v69
	v_fmac_f32_e32 v60, v22, v37
	v_fmac_f32_e32 v60, v21, v42
	v_fmac_f32_e32 v60, v20, v41
	v_fmac_f32_e32 v60, v26, v40
	v_fmac_f32_e32 v60, v25, v39
	v_fmac_f32_e32 v60, v24, v38
	v_fmac_f32_e32 v60, v23, v47
	v_fmac_f32_e32 v60, v28, v45
	v_fmac_f32_e32 v60, v31, v43
	v_fmac_f32_e32 v60, v30, v50
	v_fmac_f32_e32 v60, v29, v49
	v_fmac_f32_e32 v60, v34, v48
	s_waitcnt lgkmcnt(7)
	v_lshlrev_b32_e32 v44, 16, v91
	v_fmac_f32_e32 v60, v33, v46
	v_fmac_f32_e32 v60, v32, v44
	v_lshl_add_u32 v53, v83, 10, v36
	v_or_b32_e32 v73, 17, v61
	ds_write_b32 v53, v60 offset:49152
	v_lshl_add_u32 v53, v73, 9, v62
	ds_read_u16 v53, v53
	v_or_b32_e32 v74, 18, v61
	v_lshl_add_u32 v54, v74, 9, v62
	v_or_b32_e32 v75, 19, v61
	ds_read_u16 v54, v54
	v_lshl_add_u32 v55, v75, 9, v62
	v_or_b32_e32 v76, 20, v61
	ds_read_u16 v55, v55
	v_lshl_add_u32 v56, v76, 9, v62
	v_or_b32_e32 v77, 21, v61
	ds_read_u16 v56, v56
	v_lshl_add_u32 v57, v77, 9, v62
	v_or_b32_e32 v84, 22, v61
	ds_read_u16 v57, v57
	s_waitcnt lgkmcnt(4)
	v_lshlrev_b32_e32 v79, 16, v53
	v_lshl_add_u32 v53, v84, 9, v62
	ds_read_u16 v53, v53
	v_fma_f32 v71, v3, v71, v35
	s_waitcnt lgkmcnt(4)
	v_lshlrev_b32_e32 v80, 16, v54
	v_fmac_f32_e32 v71, v2, v79
	s_waitcnt lgkmcnt(3)
	v_lshlrev_b32_e32 v81, 16, v55
	v_or_b32_e32 v85, 23, v61
	v_fmac_f32_e32 v71, v1, v80
	s_waitcnt lgkmcnt(2)
	v_lshlrev_b32_e32 v82, 16, v56
	v_lshl_add_u32 v54, v85, 9, v62
	v_fmac_f32_e32 v71, v0, v81
	s_waitcnt lgkmcnt(1)
	v_lshlrev_b32_e32 v83, 16, v57
	ds_read_u16 v54, v54
	ds_read_u16 v55, v78 offset:23552
	ds_read_u16 v56, v78 offset:24064
	ds_read_u16 v58, v78 offset:24576
	v_fmac_f32_e32 v71, v7, v82
	s_waitcnt lgkmcnt(4)
	v_lshlrev_b32_e32 v86, 16, v53
	v_fmac_f32_e32 v71, v6, v83
	s_waitcnt lgkmcnt(3)
	v_lshlrev_b32_e32 v87, 16, v54
	v_fmac_f32_e32 v71, v5, v86
	v_fmac_f32_e32 v71, v4, v87
	v_fmac_f32_e32 v71, v18, v72
	v_fmac_f32_e32 v71, v17, v63
	v_fmac_f32_e32 v71, v16, v64
	v_fmac_f32_e32 v71, v15, v65
	v_fmac_f32_e32 v71, v14, v66
	v_fmac_f32_e32 v71, v13, v67
	v_fmac_f32_e32 v71, v12, v68
	v_fmac_f32_e32 v71, v9, v69
	v_fmac_f32_e32 v71, v19, v37
	v_fmac_f32_e32 v71, v22, v42
	v_fmac_f32_e32 v71, v21, v41
	v_fmac_f32_e32 v71, v20, v40
	v_fmac_f32_e32 v71, v26, v39
	v_fmac_f32_e32 v71, v25, v38
	v_fmac_f32_e32 v71, v24, v47
	v_fmac_f32_e32 v71, v23, v45
	v_fmac_f32_e32 v71, v28, v43
	v_fmac_f32_e32 v71, v31, v50
	v_fmac_f32_e32 v71, v30, v49
	v_fmac_f32_e32 v71, v29, v48
	v_fmac_f32_e32 v71, v34, v46
	s_waitcnt lgkmcnt(2)
	v_lshlrev_b32_e32 v57, 16, v55
	v_fmac_f32_e32 v71, v33, v44
	v_fmac_f32_e32 v71, v32, v57
	s_waitcnt lgkmcnt(1)
	v_lshlrev_b32_e32 v55, 16, v56
	s_waitcnt lgkmcnt(0)
	v_lshlrev_b32_e32 v53, 16, v58
	ds_read_u16 v54, v78 offset:25088
	ds_read_u16 v56, v78 offset:25600
	ds_read_u16 v58, v78 offset:26112
	ds_read_u16 v88, v78 offset:26624
	ds_read_u16 v89, v78 offset:27136
	ds_write_b32 v70, v71 offset:49152
	v_fma_f32 v70, v3, v79, v35
	v_fmac_f32_e32 v70, v2, v80
	v_fmac_f32_e32 v70, v1, v81
	v_fmac_f32_e32 v70, v0, v82
	v_fmac_f32_e32 v70, v7, v83
	v_fmac_f32_e32 v70, v6, v86
	v_fmac_f32_e32 v70, v5, v87
	v_fmac_f32_e32 v70, v4, v72
	v_fmac_f32_e32 v70, v18, v63
	v_fmac_f32_e32 v70, v17, v64
	v_fmac_f32_e32 v70, v16, v65
	v_fmac_f32_e32 v70, v15, v66
	v_fmac_f32_e32 v70, v14, v67
	v_fmac_f32_e32 v70, v13, v68
	v_fmac_f32_e32 v70, v12, v69
	v_fmac_f32_e32 v70, v9, v37
	v_fmac_f32_e32 v70, v19, v42
	v_fmac_f32_e32 v70, v22, v41
	v_fmac_f32_e32 v70, v21, v40
	v_fmac_f32_e32 v70, v20, v39
	v_fmac_f32_e32 v70, v26, v38
	v_fmac_f32_e32 v70, v25, v47
	v_fmac_f32_e32 v70, v24, v45
	v_fmac_f32_e32 v70, v23, v43
	v_fmac_f32_e32 v70, v28, v50
	v_fmac_f32_e32 v70, v31, v49
	v_fmac_f32_e32 v70, v30, v48
	v_fmac_f32_e32 v70, v29, v46
	v_fmac_f32_e32 v70, v34, v44
	v_fmac_f32_e32 v70, v33, v57
	v_fmac_f32_e32 v70, v32, v55
	v_lshl_add_u32 v71, v73, 10, v36
	ds_write_b32 v71, v70 offset:49152
	v_fma_f32 v70, v3, v80, v35
	v_fmac_f32_e32 v70, v2, v81
	v_fmac_f32_e32 v70, v1, v82
	v_fmac_f32_e32 v70, v0, v83
	v_fmac_f32_e32 v70, v7, v86
	v_fmac_f32_e32 v70, v6, v87
	v_fmac_f32_e32 v70, v5, v72
	v_fmac_f32_e32 v70, v4, v63
	v_fmac_f32_e32 v70, v18, v64
	v_fmac_f32_e32 v70, v17, v65
	v_fmac_f32_e32 v70, v16, v66
	v_fmac_f32_e32 v70, v15, v67
	v_fmac_f32_e32 v70, v14, v68
	v_fmac_f32_e32 v70, v13, v69
	v_fmac_f32_e32 v70, v12, v37
	v_fmac_f32_e32 v70, v9, v42
	v_fmac_f32_e32 v70, v19, v41
	v_fmac_f32_e32 v70, v22, v40
	v_fmac_f32_e32 v70, v21, v39
	v_fmac_f32_e32 v70, v20, v38
	v_fmac_f32_e32 v70, v26, v47
	v_fmac_f32_e32 v70, v25, v45
	v_fmac_f32_e32 v70, v24, v43
	v_fmac_f32_e32 v70, v23, v50
	v_fmac_f32_e32 v70, v28, v49
	v_fmac_f32_e32 v70, v31, v48
	v_fmac_f32_e32 v70, v30, v46
	v_fmac_f32_e32 v70, v29, v44
	v_fmac_f32_e32 v70, v34, v57
	v_fmac_f32_e32 v70, v33, v55
	v_fmac_f32_e32 v70, v32, v53
	v_lshl_add_u32 v71, v74, 10, v36
	ds_write_b32 v71, v70 offset:49152
	v_fma_f32 v70, v3, v81, v35
	v_fmac_f32_e32 v70, v2, v82
	v_fmac_f32_e32 v70, v1, v83
	v_fmac_f32_e32 v70, v0, v86
	v_fmac_f32_e32 v70, v7, v87
	v_fmac_f32_e32 v70, v6, v72
	v_fmac_f32_e32 v70, v5, v63
	v_fmac_f32_e32 v70, v4, v64
	v_fmac_f32_e32 v70, v18, v65
	v_fmac_f32_e32 v70, v17, v66
	v_fmac_f32_e32 v70, v16, v67
	v_fmac_f32_e32 v70, v15, v68
	v_fmac_f32_e32 v70, v14, v69
	v_fmac_f32_e32 v70, v13, v37
	v_fmac_f32_e32 v70, v12, v42
	v_fmac_f32_e32 v70, v9, v41
	v_fmac_f32_e32 v70, v19, v40
	v_fmac_f32_e32 v70, v22, v39
	v_fmac_f32_e32 v70, v21, v38
	v_fmac_f32_e32 v70, v20, v47
	v_fmac_f32_e32 v70, v26, v45
	v_fmac_f32_e32 v70, v25, v43
	v_fmac_f32_e32 v70, v24, v50
	v_fmac_f32_e32 v70, v23, v49
	v_fmac_f32_e32 v70, v28, v48
	v_fmac_f32_e32 v70, v31, v46
	v_fmac_f32_e32 v70, v30, v44
	v_fmac_f32_e32 v70, v29, v57
	v_fmac_f32_e32 v70, v34, v55
	s_waitcnt lgkmcnt(7)
	v_lshlrev_b32_e32 v60, 16, v54
	v_fmac_f32_e32 v70, v33, v53
	v_fmac_f32_e32 v70, v32, v60
	v_lshl_add_u32 v71, v75, 10, v36
	ds_write_b32 v71, v70 offset:49152
	v_fma_f32 v70, v3, v82, v35
	v_fmac_f32_e32 v70, v2, v83
	v_fmac_f32_e32 v70, v1, v86
	v_fmac_f32_e32 v70, v0, v87
	v_fmac_f32_e32 v70, v7, v72
	v_fmac_f32_e32 v70, v6, v63
	v_fmac_f32_e32 v70, v5, v64
	v_fmac_f32_e32 v70, v4, v65
	v_fmac_f32_e32 v70, v18, v66
	v_fmac_f32_e32 v70, v17, v67
	v_fmac_f32_e32 v70, v16, v68
	v_fmac_f32_e32 v70, v15, v69
	v_fmac_f32_e32 v70, v14, v37
	v_fmac_f32_e32 v70, v13, v42
	v_fmac_f32_e32 v70, v12, v41
	v_fmac_f32_e32 v70, v9, v40
	v_fmac_f32_e32 v70, v19, v39
	v_fmac_f32_e32 v70, v22, v38
	v_fmac_f32_e32 v70, v21, v47
	v_fmac_f32_e32 v70, v20, v45
	v_fmac_f32_e32 v70, v26, v43
	v_fmac_f32_e32 v70, v25, v50
	v_fmac_f32_e32 v70, v24, v49
	v_fmac_f32_e32 v70, v23, v48
	v_fmac_f32_e32 v70, v28, v46
	v_fmac_f32_e32 v70, v31, v44
	v_fmac_f32_e32 v70, v30, v57
	v_fmac_f32_e32 v70, v29, v55
	v_fmac_f32_e32 v70, v34, v53
	s_waitcnt lgkmcnt(7)
	v_lshlrev_b32_e32 v59, 16, v56
	v_fmac_f32_e32 v70, v33, v60
	v_fmac_f32_e32 v70, v32, v59
	v_lshl_add_u32 v71, v76, 10, v36
	ds_write_b32 v71, v70 offset:49152
	v_fma_f32 v70, v3, v83, v35
	v_fmac_f32_e32 v70, v2, v86
	v_fmac_f32_e32 v70, v1, v87
	v_fmac_f32_e32 v70, v0, v72
	v_fmac_f32_e32 v70, v7, v63
	v_fmac_f32_e32 v70, v6, v64
	v_fmac_f32_e32 v70, v5, v65
	v_fmac_f32_e32 v70, v4, v66
	v_fmac_f32_e32 v70, v18, v67
	v_fmac_f32_e32 v70, v17, v68
	v_fmac_f32_e32 v70, v16, v69
	v_fmac_f32_e32 v70, v15, v37
	v_fmac_f32_e32 v70, v14, v42
	v_fmac_f32_e32 v70, v13, v41
	v_fmac_f32_e32 v70, v12, v40
	v_fmac_f32_e32 v70, v9, v39
	v_fmac_f32_e32 v70, v19, v38
	v_fmac_f32_e32 v70, v22, v47
	v_fmac_f32_e32 v70, v21, v45
	v_fmac_f32_e32 v70, v20, v43
	v_fmac_f32_e32 v70, v26, v50
	v_fmac_f32_e32 v70, v25, v49
	v_fmac_f32_e32 v70, v24, v48
	v_fmac_f32_e32 v70, v23, v46
	v_fmac_f32_e32 v70, v28, v44
	v_fmac_f32_e32 v70, v31, v57
	v_fmac_f32_e32 v70, v30, v55
	v_fmac_f32_e32 v70, v29, v53
	v_fmac_f32_e32 v70, v34, v60
	s_waitcnt lgkmcnt(7)
	v_lshlrev_b32_e32 v58, 16, v58
	v_fmac_f32_e32 v70, v33, v59
	v_fmac_f32_e32 v70, v32, v58
	v_lshl_add_u32 v71, v77, 10, v36
	ds_write_b32 v71, v70 offset:49152
	v_fma_f32 v70, v3, v86, v35
	v_fmac_f32_e32 v70, v2, v87
	v_fmac_f32_e32 v70, v1, v72
	v_fmac_f32_e32 v70, v0, v63
	v_fmac_f32_e32 v70, v7, v64
	v_fmac_f32_e32 v70, v6, v65
	v_fmac_f32_e32 v70, v5, v66
	v_fmac_f32_e32 v70, v4, v67
	v_fmac_f32_e32 v70, v18, v68
	v_fmac_f32_e32 v70, v17, v69
	v_fmac_f32_e32 v70, v16, v37
	v_fmac_f32_e32 v70, v15, v42
	v_fmac_f32_e32 v70, v14, v41
	v_fmac_f32_e32 v70, v13, v40
	v_fmac_f32_e32 v70, v12, v39
	v_fmac_f32_e32 v70, v9, v38
	v_fmac_f32_e32 v70, v19, v47
	v_fmac_f32_e32 v70, v22, v45
	v_fmac_f32_e32 v70, v21, v43
	v_fmac_f32_e32 v70, v20, v50
	v_fmac_f32_e32 v70, v26, v49
	v_fmac_f32_e32 v70, v25, v48
	v_fmac_f32_e32 v70, v24, v46
	v_fmac_f32_e32 v70, v23, v44
	v_fmac_f32_e32 v70, v28, v57
	v_fmac_f32_e32 v70, v31, v55
	v_fmac_f32_e32 v70, v30, v53
	v_fmac_f32_e32 v70, v29, v60
	v_fmac_f32_e32 v70, v34, v59
	s_waitcnt lgkmcnt(7)
	v_lshlrev_b32_e32 v56, 16, v88
	v_fmac_f32_e32 v70, v33, v58
	v_fmac_f32_e32 v70, v32, v56
	v_lshl_add_u32 v71, v84, 10, v36
	ds_write_b32 v71, v70 offset:49152
	v_fma_f32 v70, v3, v87, v35
	v_fmac_f32_e32 v70, v2, v72
	v_fmac_f32_e32 v70, v1, v63
	v_fmac_f32_e32 v70, v0, v64
	v_fmac_f32_e32 v70, v7, v65
	v_fmac_f32_e32 v70, v6, v66
	v_fmac_f32_e32 v70, v5, v67
	v_fmac_f32_e32 v70, v4, v68
	v_fmac_f32_e32 v70, v18, v69
	v_fmac_f32_e32 v70, v17, v37
	v_fmac_f32_e32 v70, v16, v42
	v_fmac_f32_e32 v70, v15, v41
	v_fmac_f32_e32 v70, v14, v40
	v_fmac_f32_e32 v70, v13, v39
	v_fmac_f32_e32 v70, v12, v38
	v_fmac_f32_e32 v70, v9, v47
	v_fmac_f32_e32 v70, v19, v45
	v_fmac_f32_e32 v70, v22, v43
	v_fmac_f32_e32 v70, v21, v50
	v_fmac_f32_e32 v70, v20, v49
	v_fmac_f32_e32 v70, v26, v48
	v_fmac_f32_e32 v70, v25, v46
	v_fmac_f32_e32 v70, v24, v44
	v_fmac_f32_e32 v70, v23, v57
	v_fmac_f32_e32 v70, v28, v55
	v_fmac_f32_e32 v70, v31, v53
	v_fmac_f32_e32 v70, v30, v60
	v_fmac_f32_e32 v70, v29, v59
	v_fmac_f32_e32 v70, v34, v58
	s_waitcnt lgkmcnt(7)
	v_lshlrev_b32_e32 v54, 16, v89
	v_fmac_f32_e32 v70, v33, v56
	v_fmac_f32_e32 v70, v32, v54
	v_lshl_add_u32 v63, v85, 10, v36
	v_or_b32_e32 v75, 25, v61
	v_or_b32_e32 v71, 27, v61
	ds_write_b32 v63, v70 offset:49152
	v_lshl_add_u32 v63, v75, 9, v62
	v_lshl_add_u32 v65, v71, 9, v62
	ds_read_u16 v63, v63
	ds_read_u16 v65, v65
	v_or_b32_e32 v73, 26, v61
	v_lshl_add_u32 v64, v73, 9, v62
	ds_read_u16 v64, v64
	v_or_b32_e32 v69, 28, v61
	v_or_b32_e32 v67, 29, v61
	v_lshl_add_u32 v66, v69, 9, v62
	v_lshl_add_u32 v68, v67, 9, v62
	ds_read_u16 v66, v66
	ds_read_u16 v68, v68
	s_waitcnt lgkmcnt(3)
	v_lshlrev_b32_e32 v74, 16, v65
	v_or_b32_e32 v65, 30, v61
	v_lshl_add_u32 v61, v65, 9, v62
	v_lshlrev_b32_e32 v77, 16, v63
	ds_read_u16 v63, v61
	v_fma_f32 v52, v3, v52, v35
	s_waitcnt lgkmcnt(3)
	v_lshlrev_b32_e32 v76, 16, v64
	v_fmac_f32_e32 v52, v2, v77
	v_or_b32_e32 v61, 31, v27
	v_fmac_f32_e32 v52, v1, v76
	s_waitcnt lgkmcnt(2)
	v_lshlrev_b32_e32 v72, 16, v66
	v_lshl_add_u32 v62, v61, 9, v62
	v_fmac_f32_e32 v52, v0, v74
	s_waitcnt lgkmcnt(1)
	v_lshlrev_b32_e32 v70, 16, v68
	ds_read_u16 v62, v62
	ds_read_u16 v64, v78 offset:27648
	ds_read_u16 v79, v78 offset:28160
	ds_read_u16 v80, v78 offset:28672
	v_fmac_f32_e32 v52, v7, v72
	s_waitcnt lgkmcnt(4)
	v_lshlrev_b32_e32 v68, 16, v63
	v_fmac_f32_e32 v52, v6, v70
	s_waitcnt lgkmcnt(3)
	v_lshlrev_b32_e32 v66, 16, v62
	v_fmac_f32_e32 v52, v5, v68
	v_fmac_f32_e32 v52, v4, v66
	v_fmac_f32_e32 v52, v18, v37
	v_fmac_f32_e32 v52, v17, v42
	v_fmac_f32_e32 v52, v16, v41
	v_fmac_f32_e32 v52, v15, v40
	v_fmac_f32_e32 v52, v14, v39
	v_fmac_f32_e32 v52, v13, v38
	v_fmac_f32_e32 v52, v12, v47
	v_fmac_f32_e32 v52, v9, v45
	v_fmac_f32_e32 v52, v19, v43
	v_fmac_f32_e32 v52, v22, v50
	v_fmac_f32_e32 v52, v21, v49
	v_fmac_f32_e32 v52, v20, v48
	v_fmac_f32_e32 v52, v26, v46
	v_fmac_f32_e32 v52, v25, v44
	v_fmac_f32_e32 v52, v24, v57
	v_fmac_f32_e32 v52, v23, v55
	v_fmac_f32_e32 v52, v28, v53
	v_fmac_f32_e32 v52, v31, v60
	v_fmac_f32_e32 v52, v30, v59
	v_fmac_f32_e32 v52, v29, v58
	v_fmac_f32_e32 v52, v34, v56
	s_waitcnt lgkmcnt(2)
	v_lshlrev_b32_e32 v64, 16, v64
	v_fmac_f32_e32 v52, v33, v54
	v_fmac_f32_e32 v52, v32, v64
	s_waitcnt lgkmcnt(1)
	v_lshlrev_b32_e32 v63, 16, v79
	s_waitcnt lgkmcnt(0)
	v_lshlrev_b32_e32 v62, 16, v80
	ds_read_u16 v79, v78 offset:29184
	ds_read_u16 v80, v78 offset:29696
	ds_read_u16 v81, v78 offset:30208
	ds_read_u16 v82, v78 offset:30720
	ds_read_u16 v78, v78 offset:31232
	ds_write_b32 v51, v52 offset:49152
	v_fma_f32 v51, v3, v77, v35
	v_fmac_f32_e32 v51, v2, v76
	v_fmac_f32_e32 v51, v1, v74
	v_fmac_f32_e32 v51, v0, v72
	v_fmac_f32_e32 v51, v7, v70
	v_fmac_f32_e32 v51, v6, v68
	v_fmac_f32_e32 v51, v5, v66
	v_fmac_f32_e32 v51, v4, v37
	v_fmac_f32_e32 v51, v18, v42
	v_fmac_f32_e32 v51, v17, v41
	v_fmac_f32_e32 v51, v16, v40
	v_fmac_f32_e32 v51, v15, v39
	v_fmac_f32_e32 v51, v14, v38
	v_fmac_f32_e32 v51, v13, v47
	v_fmac_f32_e32 v51, v12, v45
	v_fmac_f32_e32 v51, v9, v43
	v_fmac_f32_e32 v51, v19, v50
	v_fmac_f32_e32 v51, v22, v49
	v_fmac_f32_e32 v51, v21, v48
	v_fmac_f32_e32 v51, v20, v46
	v_fmac_f32_e32 v51, v26, v44
	v_fmac_f32_e32 v51, v25, v57
	v_fmac_f32_e32 v51, v24, v55
	v_fmac_f32_e32 v51, v23, v53
	v_fmac_f32_e32 v51, v28, v60
	v_fmac_f32_e32 v51, v31, v59
	v_fmac_f32_e32 v51, v30, v58
	v_fmac_f32_e32 v51, v29, v56
	v_fmac_f32_e32 v51, v34, v54
	v_fmac_f32_e32 v51, v33, v64
	v_fmac_f32_e32 v51, v32, v63
	v_lshl_add_u32 v52, v75, 10, v36
	ds_write_b32 v52, v51 offset:49152
	v_fma_f32 v51, v3, v76, v35
	v_fmac_f32_e32 v51, v2, v74
	v_fmac_f32_e32 v51, v1, v72
	v_fmac_f32_e32 v51, v0, v70
	v_fmac_f32_e32 v51, v7, v68
	v_fmac_f32_e32 v51, v6, v66
	v_fmac_f32_e32 v51, v5, v37
	v_fmac_f32_e32 v51, v4, v42
	v_fmac_f32_e32 v51, v18, v41
	v_fmac_f32_e32 v51, v17, v40
	v_fmac_f32_e32 v51, v16, v39
	v_fmac_f32_e32 v51, v15, v38
	v_fmac_f32_e32 v51, v14, v47
	v_fmac_f32_e32 v51, v13, v45
	v_fmac_f32_e32 v51, v12, v43
	v_fmac_f32_e32 v51, v9, v50
	v_fmac_f32_e32 v51, v19, v49
	v_fmac_f32_e32 v51, v22, v48
	v_fmac_f32_e32 v51, v21, v46
	v_fmac_f32_e32 v51, v20, v44
	v_fmac_f32_e32 v51, v26, v57
	v_fmac_f32_e32 v51, v25, v55
	v_fmac_f32_e32 v51, v24, v53
	v_fmac_f32_e32 v51, v23, v60
	v_fmac_f32_e32 v51, v28, v59
	v_fmac_f32_e32 v51, v31, v58
	v_fmac_f32_e32 v51, v30, v56
	v_fmac_f32_e32 v51, v29, v54
	v_fmac_f32_e32 v51, v34, v64
	v_fmac_f32_e32 v51, v33, v63
	v_fmac_f32_e32 v51, v32, v62
	v_lshl_add_u32 v52, v73, 10, v36
	ds_write_b32 v52, v51 offset:49152
	v_fma_f32 v51, v3, v74, v35
	v_fmac_f32_e32 v51, v2, v72
	v_fmac_f32_e32 v51, v1, v70
	v_fmac_f32_e32 v51, v0, v68
	v_fmac_f32_e32 v51, v7, v66
	v_fmac_f32_e32 v51, v6, v37
	v_fmac_f32_e32 v51, v5, v42
	v_fmac_f32_e32 v51, v4, v41
	v_fmac_f32_e32 v51, v18, v40
	v_fmac_f32_e32 v51, v17, v39
	v_fmac_f32_e32 v51, v16, v38
	v_fmac_f32_e32 v51, v15, v47
	v_fmac_f32_e32 v51, v14, v45
	v_fmac_f32_e32 v51, v13, v43
	v_fmac_f32_e32 v51, v12, v50
	v_fmac_f32_e32 v51, v9, v49
	v_fmac_f32_e32 v51, v19, v48
	v_fmac_f32_e32 v51, v22, v46
	v_fmac_f32_e32 v51, v21, v44
	v_fmac_f32_e32 v51, v20, v57
	v_fmac_f32_e32 v51, v26, v55
	v_fmac_f32_e32 v51, v25, v53
	v_fmac_f32_e32 v51, v24, v60
	v_fmac_f32_e32 v51, v23, v59
	v_fmac_f32_e32 v51, v28, v58
	v_fmac_f32_e32 v51, v31, v56
	v_fmac_f32_e32 v51, v30, v54
	v_fmac_f32_e32 v51, v29, v64
	v_fmac_f32_e32 v51, v34, v63
	s_waitcnt lgkmcnt(7)
	v_lshlrev_b32_e32 v84, 16, v79
	v_fmac_f32_e32 v51, v33, v62
	v_fmac_f32_e32 v51, v32, v84
	v_lshl_add_u32 v52, v71, 10, v36
	ds_write_b32 v52, v51 offset:49152
	v_fma_f32 v51, v3, v72, v35
	v_fmac_f32_e32 v51, v2, v70
	v_fmac_f32_e32 v51, v1, v68
	v_fmac_f32_e32 v51, v0, v66
	v_fmac_f32_e32 v51, v7, v37
	v_fmac_f32_e32 v51, v6, v42
	v_fmac_f32_e32 v51, v5, v41
	v_fmac_f32_e32 v51, v4, v40
	v_fmac_f32_e32 v51, v18, v39
	v_fmac_f32_e32 v51, v17, v38
	v_fmac_f32_e32 v51, v16, v47
	v_fmac_f32_e32 v51, v15, v45
	v_fmac_f32_e32 v51, v14, v43
	v_fmac_f32_e32 v51, v13, v50
	v_fmac_f32_e32 v51, v12, v49
	v_fmac_f32_e32 v51, v9, v48
	v_fmac_f32_e32 v51, v19, v46
	v_fmac_f32_e32 v51, v22, v44
	v_fmac_f32_e32 v51, v21, v57
	v_fmac_f32_e32 v51, v20, v55
	v_fmac_f32_e32 v51, v26, v53
	v_fmac_f32_e32 v51, v25, v60
	v_fmac_f32_e32 v51, v24, v59
	v_fmac_f32_e32 v51, v23, v58
	v_fmac_f32_e32 v51, v28, v56
	v_fmac_f32_e32 v51, v31, v54
	v_fmac_f32_e32 v51, v30, v64
	v_fmac_f32_e32 v51, v29, v63
	v_fmac_f32_e32 v51, v34, v62
	s_waitcnt lgkmcnt(7)
	v_lshlrev_b32_e32 v83, 16, v80
	v_fmac_f32_e32 v51, v33, v84
	v_fmac_f32_e32 v51, v32, v83
	v_lshl_add_u32 v52, v69, 10, v36
	ds_write_b32 v52, v51 offset:49152
	v_fma_f32 v51, v3, v70, v35
	v_fmac_f32_e32 v51, v2, v68
	v_fmac_f32_e32 v51, v1, v66
	v_fmac_f32_e32 v51, v0, v37
	v_fmac_f32_e32 v51, v7, v42
	v_fmac_f32_e32 v51, v6, v41
	v_fmac_f32_e32 v51, v5, v40
	v_fmac_f32_e32 v51, v4, v39
	v_fmac_f32_e32 v51, v18, v38
	v_fmac_f32_e32 v51, v17, v47
	v_fmac_f32_e32 v51, v16, v45
	v_fmac_f32_e32 v51, v15, v43
	v_fmac_f32_e32 v51, v14, v50
	v_fmac_f32_e32 v51, v13, v49
	v_fmac_f32_e32 v51, v12, v48
	v_fmac_f32_e32 v51, v9, v46
	v_fmac_f32_e32 v51, v19, v44
	v_fmac_f32_e32 v51, v22, v57
	v_fmac_f32_e32 v51, v21, v55
	v_fmac_f32_e32 v51, v20, v53
	v_fmac_f32_e32 v51, v26, v60
	v_fmac_f32_e32 v51, v25, v59
	v_fmac_f32_e32 v51, v24, v58
	v_fmac_f32_e32 v51, v23, v56
	v_fmac_f32_e32 v51, v28, v54
	v_fmac_f32_e32 v51, v31, v64
	v_fmac_f32_e32 v51, v30, v63
	v_fmac_f32_e32 v51, v29, v62
	v_fmac_f32_e32 v51, v34, v84
	s_waitcnt lgkmcnt(7)
	v_lshlrev_b32_e32 v80, 16, v81
	v_fmac_f32_e32 v51, v33, v83
	v_fmac_f32_e32 v51, v32, v80
	v_lshl_add_u32 v52, v67, 10, v36
	ds_write_b32 v52, v51 offset:49152
	v_fma_f32 v51, v3, v68, v35
	v_fmac_f32_e32 v35, v3, v66
	v_fmac_f32_e32 v51, v2, v66
	v_fmac_f32_e32 v35, v2, v37
	v_fmac_f32_e32 v51, v1, v37
	v_fmac_f32_e32 v35, v1, v42
	v_fmac_f32_e32 v51, v0, v42
	v_fmac_f32_e32 v35, v0, v41
	v_fmac_f32_e32 v51, v7, v41
	v_fmac_f32_e32 v35, v7, v40
	v_fmac_f32_e32 v51, v6, v40
	v_fmac_f32_e32 v35, v6, v39
	v_fmac_f32_e32 v51, v5, v39
	v_fmac_f32_e32 v35, v5, v38
	v_fmac_f32_e32 v51, v4, v38
	v_fmac_f32_e32 v35, v4, v47
	v_fmac_f32_e32 v51, v18, v47
	v_fmac_f32_e32 v35, v18, v45
	v_fmac_f32_e32 v51, v17, v45
	v_fmac_f32_e32 v35, v17, v43
	v_fmac_f32_e32 v51, v16, v43
	v_fmac_f32_e32 v35, v16, v50
	v_fmac_f32_e32 v51, v15, v50
	v_fmac_f32_e32 v35, v15, v49
	v_fmac_f32_e32 v51, v14, v49
	v_fmac_f32_e32 v35, v14, v48
	v_fmac_f32_e32 v51, v13, v48
	v_fmac_f32_e32 v35, v13, v46
	v_fmac_f32_e32 v51, v12, v46
	v_fmac_f32_e32 v35, v12, v44
	v_fmac_f32_e32 v51, v9, v44
	v_fmac_f32_e32 v35, v9, v57
	v_fmac_f32_e32 v51, v19, v57
	v_fmac_f32_e32 v35, v19, v55
	v_fmac_f32_e32 v51, v22, v55
	v_fmac_f32_e32 v35, v22, v53
	v_fmac_f32_e32 v51, v21, v53
	v_fmac_f32_e32 v35, v21, v60
	v_fmac_f32_e32 v51, v20, v60
	v_fmac_f32_e32 v35, v20, v59
	v_fmac_f32_e32 v51, v26, v59
	v_fmac_f32_e32 v35, v26, v58
	v_fmac_f32_e32 v51, v25, v58
	v_fmac_f32_e32 v35, v25, v56
	v_fmac_f32_e32 v51, v24, v56
	v_fmac_f32_e32 v35, v24, v54
	v_fmac_f32_e32 v51, v23, v54
	v_fmac_f32_e32 v35, v23, v64
	v_fmac_f32_e32 v51, v28, v64
	v_fmac_f32_e32 v35, v28, v63
	v_fmac_f32_e32 v51, v31, v63
	v_fmac_f32_e32 v35, v31, v62
	v_fmac_f32_e32 v51, v30, v62
	v_fmac_f32_e32 v35, v30, v84
	v_fmac_f32_e32 v51, v29, v84
	v_fmac_f32_e32 v35, v29, v83
	s_waitcnt lgkmcnt(7)
	v_lshlrev_b32_e32 v79, 16, v82
	v_fmac_f32_e32 v51, v34, v83
	v_fmac_f32_e32 v35, v34, v80
	s_waitcnt lgkmcnt(6)
	v_lshlrev_b32_e32 v78, 16, v78
	v_fmac_f32_e32 v51, v33, v80
	v_fmac_f32_e32 v35, v33, v79
	v_fmac_f32_e32 v51, v32, v79
	v_lshl_add_u32 v52, v65, 10, v36
	v_fmac_f32_e32 v35, v32, v78
	v_lshl_add_u32 v0, v61, 10, v36
	ds_write_b32 v52, v51 offset:49152
	ds_write_b32 v0, v35 offset:49152
	v_lshlrev_b32_e32 v0, 4, v8
	v_and_b32_e32 v4, 0x3f0, v0
	s_waitcnt lgkmcnt(0)
	s_barrier
	global_load_dwordx4 v[0:3], v4, s[4:5]
	s_nop 0
	global_load_dwordx4 v[4:7], v4, s[6:7]
	v_and_b32_e32 v12, -8, v27
	v_ashrrev_i32_e32 v13, 31, v12
	v_lshl_add_u64 v[12:13], s[8:9], 0, v[12:13]
	v_lshlrev_b64 v[12:13], 11, v[12:13]
	v_and_b32_e32 v14, 63, v8
	v_lshl_or_b32 v12, v14, 3, v12
	v_lshl_add_u64 v[8:9], s[24:25], 0, v[12:13]
	v_lshlrev_b32_e32 v12, 10, v27
	v_lshlrev_b32_e32 v13, 4, v14
	s_movk_i32 s8, 0xe000
	v_and_or_b32 v12, v12, s8, v13
	s_add_i32 s8, 0, 0xc000
	v_add_u32_e32 v12, s8, v12
	s_waitcnt vmcnt(0)
	ds_read_b128 v[28:31], v12
	ds_read_b128 v[32:35], v12 offset:1024
	ds_read_b128 v[38:41], v12 offset:2048
	ds_read_b128 v[44:47], v12 offset:3072
	ds_read_b128 v[54:57], v12 offset:4096
	ds_read_b128 v[62:65], v12 offset:5120
	ds_read_b128 v[78:81], v12 offset:6144
	ds_read_b128 v[88:91], v12 offset:7168
	s_mov_b64 s[8:9], 0x800
	s_waitcnt lgkmcnt(0)
	v_add_f32_e32 v48, v29, v28
	v_add_f32_e32 v53, v30, v31
	v_add_f32_e32 v13, v48, v53
	v_add_f32_e32 v48, v33, v32
	v_add_f32_e32 v53, v34, v35
	v_add_f32_e32 v14, v48, v53
	v_add_f32_e32 v48, v39, v38
	v_add_f32_e32 v53, v40, v41
	v_add_f32_e32 v15, v48, v53
	v_add_f32_e32 v48, v45, v44
	v_add_f32_e32 v53, v46, v47
	v_add_f32_e32 v16, v48, v53
	v_add_f32_e32 v48, v55, v54
	v_add_f32_e32 v53, v56, v57
	v_add_f32_e32 v17, v48, v53
	v_add_f32_e32 v48, v63, v62
	v_add_f32_e32 v53, v64, v65
	v_add_f32_e32 v18, v48, v53
	v_add_f32_e32 v48, v79, v78
	v_add_f32_e32 v53, v80, v81
	v_add_f32_e32 v19, v48, v53
	v_add_f32_e32 v48, v89, v88
	v_add_f32_e32 v53, v90, v91
	v_add_f32_e32 v20, v48, v53
	ds_bpermute_b32 v21, v202, v13
	ds_bpermute_b32 v22, v202, v14
	ds_bpermute_b32 v23, v202, v15
	ds_bpermute_b32 v24, v202, v16
	ds_bpermute_b32 v25, v202, v17
	ds_bpermute_b32 v26, v202, v18
	ds_bpermute_b32 v37, v202, v19
	ds_bpermute_b32 v43, v202, v20
	s_waitcnt lgkmcnt(0)
	v_add_f32_e32 v13, v13, v21
	v_add_f32_e32 v14, v14, v22
	v_add_f32_e32 v15, v15, v23
	v_add_f32_e32 v16, v16, v24
	v_add_f32_e32 v17, v17, v25
	v_add_f32_e32 v18, v18, v26
	v_add_f32_e32 v19, v19, v37
	v_add_f32_e32 v20, v20, v43
	ds_bpermute_b32 v21, v203, v13
	ds_bpermute_b32 v22, v203, v14
	ds_bpermute_b32 v23, v203, v15
	ds_bpermute_b32 v24, v203, v16
	ds_bpermute_b32 v25, v203, v17
	ds_bpermute_b32 v26, v203, v18
	ds_bpermute_b32 v37, v203, v19
	ds_bpermute_b32 v43, v203, v20
	s_waitcnt lgkmcnt(0)
	v_add_f32_e32 v13, v13, v21
	v_add_f32_e32 v14, v14, v22
	v_add_f32_e32 v15, v15, v23
	v_add_f32_e32 v16, v16, v24
	v_add_f32_e32 v17, v17, v25
	v_add_f32_e32 v18, v18, v26
	v_add_f32_e32 v19, v19, v37
	v_add_f32_e32 v20, v20, v43
	ds_bpermute_b32 v21, v204, v13
	ds_bpermute_b32 v22, v204, v14
	ds_bpermute_b32 v23, v204, v15
	ds_bpermute_b32 v24, v204, v16
	ds_bpermute_b32 v25, v204, v17
	ds_bpermute_b32 v26, v204, v18
	ds_bpermute_b32 v37, v204, v19
	ds_bpermute_b32 v43, v204, v20
	s_waitcnt lgkmcnt(0)
	v_add_f32_e32 v13, v13, v21
	v_add_f32_e32 v14, v14, v22
	v_add_f32_e32 v15, v15, v23
	v_add_f32_e32 v16, v16, v24
	v_add_f32_e32 v17, v17, v25
	v_add_f32_e32 v18, v18, v26
	v_add_f32_e32 v19, v19, v37
	v_add_f32_e32 v20, v20, v43
	ds_bpermute_b32 v21, v205, v13
	ds_bpermute_b32 v22, v205, v14
	ds_bpermute_b32 v23, v205, v15
	ds_bpermute_b32 v24, v205, v16
	ds_bpermute_b32 v25, v205, v17
	ds_bpermute_b32 v26, v205, v18
	ds_bpermute_b32 v37, v205, v19
	ds_bpermute_b32 v43, v205, v20
	s_waitcnt lgkmcnt(0)
	v_add_f32_e32 v13, v13, v21
	v_add_f32_e32 v14, v14, v22
	v_add_f32_e32 v15, v15, v23
	v_add_f32_e32 v16, v16, v24
	v_add_f32_e32 v17, v17, v25
	v_add_f32_e32 v18, v18, v26
	v_add_f32_e32 v19, v19, v37
	v_add_f32_e32 v20, v20, v43
	ds_bpermute_b32 v21, v206, v13
	ds_bpermute_b32 v22, v206, v14
	ds_bpermute_b32 v23, v206, v15
	ds_bpermute_b32 v24, v206, v16
	ds_bpermute_b32 v25, v206, v17
	ds_bpermute_b32 v26, v206, v18
	ds_bpermute_b32 v37, v206, v19
	ds_bpermute_b32 v43, v206, v20
	s_waitcnt lgkmcnt(0)
	v_add_f32_e32 v13, v13, v21
	v_add_f32_e32 v14, v14, v22
	v_add_f32_e32 v15, v15, v23
	v_add_f32_e32 v16, v16, v24
	v_add_f32_e32 v17, v17, v25
	v_add_f32_e32 v18, v18, v26
	v_add_f32_e32 v19, v19, v37
	v_add_f32_e32 v20, v20, v43
	ds_bpermute_b32 v21, v11, v13
	ds_bpermute_b32 v22, v11, v14
	ds_bpermute_b32 v23, v11, v15
	ds_bpermute_b32 v24, v11, v16
	ds_bpermute_b32 v25, v11, v17
	ds_bpermute_b32 v26, v11, v18
	ds_bpermute_b32 v37, v11, v19
	ds_bpermute_b32 v43, v11, v20
	s_waitcnt lgkmcnt(0)
	v_add_f32_e32 v13, v13, v21
	v_add_f32_e32 v14, v14, v22
	v_add_f32_e32 v15, v15, v23
	v_add_f32_e32 v16, v16, v24
	v_add_f32_e32 v17, v17, v25
	v_add_f32_e32 v18, v18, v26
	v_add_f32_e32 v19, v19, v37
	v_add_f32_e32 v20, v20, v43
	v_fmamk_f32 v28, v13, 0xbb800000, v28
	v_fmamk_f32 v29, v13, 0xbb800000, v29
	v_fmamk_f32 v30, v13, 0xbb800000, v30
	v_fmamk_f32 v31, v13, 0xbb800000, v31
	v_fmamk_f32 v32, v14, 0xbb800000, v32
	v_fmamk_f32 v33, v14, 0xbb800000, v33
	v_fmamk_f32 v34, v14, 0xbb800000, v34
	v_fmamk_f32 v35, v14, 0xbb800000, v35
	v_fmamk_f32 v38, v15, 0xbb800000, v38
	v_fmamk_f32 v39, v15, 0xbb800000, v39
	v_fmamk_f32 v40, v15, 0xbb800000, v40
	v_fmamk_f32 v41, v15, 0xbb800000, v41
	v_fmamk_f32 v44, v16, 0xbb800000, v44
	v_fmamk_f32 v45, v16, 0xbb800000, v45
	v_fmamk_f32 v46, v16, 0xbb800000, v46
	v_fmamk_f32 v47, v16, 0xbb800000, v47
	v_fmamk_f32 v54, v17, 0xbb800000, v54
	v_fmamk_f32 v55, v17, 0xbb800000, v55
	v_fmamk_f32 v56, v17, 0xbb800000, v56
	v_fmamk_f32 v57, v17, 0xbb800000, v57
	v_fmamk_f32 v62, v18, 0xbb800000, v62
	v_fmamk_f32 v63, v18, 0xbb800000, v63
	v_fmamk_f32 v64, v18, 0xbb800000, v64
	v_fmamk_f32 v65, v18, 0xbb800000, v65
	v_fmamk_f32 v78, v19, 0xbb800000, v78
	v_fmamk_f32 v79, v19, 0xbb800000, v79
	v_fmamk_f32 v80, v19, 0xbb800000, v80
	v_fmamk_f32 v81, v19, 0xbb800000, v81
	v_fmamk_f32 v88, v20, 0xbb800000, v88
	v_fmamk_f32 v89, v20, 0xbb800000, v89
	v_fmamk_f32 v90, v20, 0xbb800000, v90
	v_fmamk_f32 v91, v20, 0xbb800000, v91
	v_mul_f32_e32 v48, v29, v29
	v_mul_f32_e32 v53, v30, v30
	v_mul_f32_e32 v21, v28, v28
	v_mul_f32_e32 v13, v31, v31
	v_add_f32_e32 v48, v48, v21
	v_add_f32_e32 v53, v53, v13
	v_add_f32_e32 v13, v48, v53
	v_mul_f32_e32 v48, v33, v33
	v_mul_f32_e32 v53, v34, v34
	v_mul_f32_e32 v22, v32, v32
	v_mul_f32_e32 v14, v35, v35
	v_add_f32_e32 v48, v48, v22
	v_add_f32_e32 v53, v53, v14
	v_add_f32_e32 v14, v48, v53
	v_mul_f32_e32 v48, v39, v39
	v_mul_f32_e32 v53, v40, v40
	v_mul_f32_e32 v23, v38, v38
	v_mul_f32_e32 v15, v41, v41
	v_add_f32_e32 v48, v48, v23
	v_add_f32_e32 v53, v53, v15
	v_add_f32_e32 v15, v48, v53
	v_mul_f32_e32 v48, v45, v45
	v_mul_f32_e32 v53, v46, v46
	v_mul_f32_e32 v24, v44, v44
	v_mul_f32_e32 v16, v47, v47
	v_add_f32_e32 v48, v48, v24
	v_add_f32_e32 v53, v53, v16
	v_add_f32_e32 v16, v48, v53
	v_mul_f32_e32 v48, v55, v55
	v_mul_f32_e32 v53, v56, v56
	v_mul_f32_e32 v25, v54, v54
	v_mul_f32_e32 v17, v57, v57
	v_add_f32_e32 v48, v48, v25
	v_add_f32_e32 v53, v53, v17
	v_add_f32_e32 v17, v48, v53
	v_mul_f32_e32 v48, v63, v63
	v_mul_f32_e32 v53, v64, v64
	v_mul_f32_e32 v26, v62, v62
	v_mul_f32_e32 v18, v65, v65
	v_add_f32_e32 v48, v48, v26
	v_add_f32_e32 v53, v53, v18
	v_add_f32_e32 v18, v48, v53
	v_mul_f32_e32 v48, v79, v79
	v_mul_f32_e32 v53, v80, v80
	v_mul_f32_e32 v37, v78, v78
	v_mul_f32_e32 v19, v81, v81
	v_add_f32_e32 v48, v48, v37
	v_add_f32_e32 v53, v53, v19
	v_add_f32_e32 v19, v48, v53
	v_mul_f32_e32 v48, v89, v89
	v_mul_f32_e32 v53, v90, v90
	v_mul_f32_e32 v43, v88, v88
	v_mul_f32_e32 v20, v91, v91
	v_add_f32_e32 v48, v48, v43
	v_add_f32_e32 v53, v53, v20
	v_add_f32_e32 v20, v48, v53
	ds_bpermute_b32 v21, v202, v13
	ds_bpermute_b32 v22, v202, v14
	ds_bpermute_b32 v23, v202, v15
	ds_bpermute_b32 v24, v202, v16
	ds_bpermute_b32 v25, v202, v17
	ds_bpermute_b32 v26, v202, v18
	ds_bpermute_b32 v37, v202, v19
	ds_bpermute_b32 v43, v202, v20
	s_waitcnt lgkmcnt(0)
	v_add_f32_e32 v13, v13, v21
	v_add_f32_e32 v14, v14, v22
	v_add_f32_e32 v15, v15, v23
	v_add_f32_e32 v16, v16, v24
	v_add_f32_e32 v17, v17, v25
	v_add_f32_e32 v18, v18, v26
	v_add_f32_e32 v19, v19, v37
	v_add_f32_e32 v20, v20, v43
	ds_bpermute_b32 v21, v203, v13
	ds_bpermute_b32 v22, v203, v14
	ds_bpermute_b32 v23, v203, v15
	ds_bpermute_b32 v24, v203, v16
	ds_bpermute_b32 v25, v203, v17
	ds_bpermute_b32 v26, v203, v18
	ds_bpermute_b32 v37, v203, v19
	ds_bpermute_b32 v43, v203, v20
	s_waitcnt lgkmcnt(0)
	v_add_f32_e32 v13, v13, v21
	v_add_f32_e32 v14, v14, v22
	v_add_f32_e32 v15, v15, v23
	v_add_f32_e32 v16, v16, v24
	v_add_f32_e32 v17, v17, v25
	v_add_f32_e32 v18, v18, v26
	v_add_f32_e32 v19, v19, v37
	v_add_f32_e32 v20, v20, v43
	ds_bpermute_b32 v21, v204, v13
	ds_bpermute_b32 v22, v204, v14
	ds_bpermute_b32 v23, v204, v15
	ds_bpermute_b32 v24, v204, v16
	ds_bpermute_b32 v25, v204, v17
	ds_bpermute_b32 v26, v204, v18
	ds_bpermute_b32 v37, v204, v19
	ds_bpermute_b32 v43, v204, v20
	s_waitcnt lgkmcnt(0)
	v_add_f32_e32 v13, v13, v21
	v_add_f32_e32 v14, v14, v22
	v_add_f32_e32 v15, v15, v23
	v_add_f32_e32 v16, v16, v24
	v_add_f32_e32 v17, v17, v25
	v_add_f32_e32 v18, v18, v26
	v_add_f32_e32 v19, v19, v37
	v_add_f32_e32 v20, v20, v43
	ds_bpermute_b32 v21, v205, v13
	ds_bpermute_b32 v22, v205, v14
	ds_bpermute_b32 v23, v205, v15
	ds_bpermute_b32 v24, v205, v16
	ds_bpermute_b32 v25, v205, v17
	ds_bpermute_b32 v26, v205, v18
	ds_bpermute_b32 v37, v205, v19
	ds_bpermute_b32 v43, v205, v20
	s_waitcnt lgkmcnt(0)
	v_add_f32_e32 v13, v13, v21
	v_add_f32_e32 v14, v14, v22
	v_add_f32_e32 v15, v15, v23
	v_add_f32_e32 v16, v16, v24
	v_add_f32_e32 v17, v17, v25
	v_add_f32_e32 v18, v18, v26
	v_add_f32_e32 v19, v19, v37
	v_add_f32_e32 v20, v20, v43
	ds_bpermute_b32 v21, v206, v13
	ds_bpermute_b32 v22, v206, v14
	ds_bpermute_b32 v23, v206, v15
	ds_bpermute_b32 v24, v206, v16
	ds_bpermute_b32 v25, v206, v17
	ds_bpermute_b32 v26, v206, v18
	ds_bpermute_b32 v37, v206, v19
	ds_bpermute_b32 v43, v206, v20
	s_waitcnt lgkmcnt(0)
	v_add_f32_e32 v13, v13, v21
	v_add_f32_e32 v14, v14, v22
	v_add_f32_e32 v15, v15, v23
	v_add_f32_e32 v16, v16, v24
	v_add_f32_e32 v17, v17, v25
	v_add_f32_e32 v18, v18, v26
	v_add_f32_e32 v19, v19, v37
	v_add_f32_e32 v20, v20, v43
	ds_bpermute_b32 v21, v11, v13
	ds_bpermute_b32 v22, v11, v14
	ds_bpermute_b32 v23, v11, v15
	ds_bpermute_b32 v24, v11, v16
	ds_bpermute_b32 v25, v11, v17
	ds_bpermute_b32 v26, v11, v18
	ds_bpermute_b32 v37, v11, v19
	ds_bpermute_b32 v43, v11, v20
	s_waitcnt lgkmcnt(0)
	v_add_f32_e32 v13, v13, v21
	v_add_f32_e32 v14, v14, v22
	v_add_f32_e32 v15, v15, v23
	v_add_f32_e32 v16, v16, v24
	v_add_f32_e32 v17, v17, v25
	v_add_f32_e32 v18, v18, v26
	v_add_f32_e32 v19, v19, v37
	v_add_f32_e32 v20, v20, v43
	v_fmamk_f32 v13, v13, 0x3b800000, v228
	v_fmamk_f32 v14, v14, 0x3b800000, v228
	v_fmamk_f32 v15, v15, 0x3b800000, v228
	v_fmamk_f32 v16, v16, 0x3b800000, v228
	v_fmamk_f32 v17, v17, 0x3b800000, v228
	v_fmamk_f32 v18, v18, 0x3b800000, v228
	v_fmamk_f32 v19, v19, 0x3b800000, v228
	v_fmamk_f32 v20, v20, 0x3b800000, v228
	v_rsq_f32_e32 v13, v13
	v_rsq_f32_e32 v14, v14
	v_rsq_f32_e32 v15, v15
	v_rsq_f32_e32 v16, v16
	v_rsq_f32_e32 v17, v17
	v_rsq_f32_e32 v18, v18
	v_rsq_f32_e32 v19, v19
	v_rsq_f32_e32 v20, v20
	s_nop 0
	v_mul_f32_e32 v28, v28, v13
	v_mul_f32_e32 v29, v29, v13
	v_mul_f32_e32 v30, v30, v13
	v_mul_f32_e32 v31, v31, v13
	v_mul_f32_e32 v32, v32, v14
	v_mul_f32_e32 v33, v33, v14
	v_mul_f32_e32 v34, v34, v14
	v_mul_f32_e32 v35, v35, v14
	v_mul_f32_e32 v38, v38, v15
	v_mul_f32_e32 v39, v39, v15
	v_mul_f32_e32 v40, v40, v15
	v_mul_f32_e32 v41, v41, v15
	v_mul_f32_e32 v44, v44, v16
	v_mul_f32_e32 v45, v45, v16
	v_mul_f32_e32 v46, v46, v16
	v_mul_f32_e32 v47, v47, v16
	v_mul_f32_e32 v54, v54, v17
	v_mul_f32_e32 v55, v55, v17
	v_mul_f32_e32 v56, v56, v17
	v_mul_f32_e32 v57, v57, v17
	v_mul_f32_e32 v62, v62, v18
	v_mul_f32_e32 v63, v63, v18
	v_mul_f32_e32 v64, v64, v18
	v_mul_f32_e32 v65, v65, v18
	v_mul_f32_e32 v78, v78, v19
	v_mul_f32_e32 v79, v79, v19
	v_mul_f32_e32 v80, v80, v19
	v_mul_f32_e32 v81, v81, v19
	v_mul_f32_e32 v88, v88, v20
	v_mul_f32_e32 v89, v89, v20
	v_mul_f32_e32 v90, v90, v20
	v_mul_f32_e32 v91, v91, v20
	v_fma_f32 v28, v0, v28, v4
	v_fma_f32 v29, v1, v29, v5
	v_fma_f32 v30, v2, v30, v6
	v_fma_f32 v31, v3, v31, v7
	v_fma_f32 v32, v0, v32, v4
	v_fma_f32 v33, v1, v33, v5
	v_fma_f32 v34, v2, v34, v6
	v_fma_f32 v35, v3, v35, v7
	v_fma_f32 v38, v0, v38, v4
	v_fma_f32 v39, v1, v39, v5
	v_fma_f32 v40, v2, v40, v6
	v_fma_f32 v41, v3, v41, v7
	v_fma_f32 v44, v0, v44, v4
	v_fma_f32 v45, v1, v45, v5
	v_fma_f32 v46, v2, v46, v6
	v_fma_f32 v47, v3, v47, v7
	v_fma_f32 v54, v0, v54, v4
	v_fma_f32 v55, v1, v55, v5
	v_fma_f32 v56, v2, v56, v6
	v_fma_f32 v57, v3, v57, v7
	v_fma_f32 v62, v0, v62, v4
	v_fma_f32 v63, v1, v63, v5
	v_fma_f32 v64, v2, v64, v6
	v_fma_f32 v65, v3, v65, v7
	v_fma_f32 v78, v0, v78, v4
	v_fma_f32 v79, v1, v79, v5
	v_fma_f32 v80, v2, v80, v6
	v_fma_f32 v81, v3, v81, v7
	v_fma_f32 v88, v0, v88, v4
	v_fma_f32 v89, v1, v89, v5
	v_fma_f32 v90, v2, v90, v6
	v_fma_f32 v91, v3, v91, v7
	v_mul_f32_e32 v21, 0xbfb8aa3b, v28
	v_mul_f32_e32 v22, 0xbfb8aa3b, v29
	v_mul_f32_e32 v23, 0xbfb8aa3b, v30
	v_mul_f32_e32 v24, 0xbfb8aa3b, v31
	v_mul_f32_e32 v25, 0xbfb8aa3b, v32
	v_mul_f32_e32 v26, 0xbfb8aa3b, v33
	v_mul_f32_e32 v37, 0xbfb8aa3b, v34
	v_mul_f32_e32 v43, 0xbfb8aa3b, v35
	v_mul_f32_e32 v13, 0xbfb8aa3b, v38
	v_mul_f32_e32 v14, 0xbfb8aa3b, v39
	v_mul_f32_e32 v15, 0xbfb8aa3b, v40
	v_mul_f32_e32 v16, 0xbfb8aa3b, v41
	v_mul_f32_e32 v17, 0xbfb8aa3b, v44
	v_mul_f32_e32 v18, 0xbfb8aa3b, v45
	v_mul_f32_e32 v19, 0xbfb8aa3b, v46
	v_mul_f32_e32 v20, 0xbfb8aa3b, v47
	v_exp_f32_e32 v21, v21
	v_exp_f32_e32 v22, v22
	v_exp_f32_e32 v23, v23
	v_exp_f32_e32 v24, v24
	v_exp_f32_e32 v25, v25
	v_exp_f32_e32 v26, v26
	v_exp_f32_e32 v37, v37
	v_exp_f32_e32 v43, v43
	v_exp_f32_e32 v13, v13
	v_exp_f32_e32 v14, v14
	v_exp_f32_e32 v15, v15
	v_exp_f32_e32 v16, v16
	v_exp_f32_e32 v17, v17
	v_exp_f32_e32 v18, v18
	v_exp_f32_e32 v19, v19
	v_exp_f32_e32 v20, v20
	v_add_f32_e32 v21, 1.0, v21
	v_add_f32_e32 v22, 1.0, v22
	v_add_f32_e32 v23, 1.0, v23
	v_add_f32_e32 v24, 1.0, v24
	v_add_f32_e32 v25, 1.0, v25
	v_add_f32_e32 v26, 1.0, v26
	v_add_f32_e32 v37, 1.0, v37
	v_add_f32_e32 v43, 1.0, v43
	v_add_f32_e32 v13, 1.0, v13
	v_add_f32_e32 v14, 1.0, v14
	v_add_f32_e32 v15, 1.0, v15
	v_add_f32_e32 v16, 1.0, v16
	v_add_f32_e32 v17, 1.0, v17
	v_add_f32_e32 v18, 1.0, v18
	v_add_f32_e32 v19, 1.0, v19
	v_add_f32_e32 v20, 1.0, v20
	v_rcp_f32_e32 v21, v21
	v_rcp_f32_e32 v22, v22
	v_rcp_f32_e32 v23, v23
	v_rcp_f32_e32 v24, v24
	v_rcp_f32_e32 v25, v25
	v_rcp_f32_e32 v26, v26
	v_rcp_f32_e32 v37, v37
	v_rcp_f32_e32 v43, v43
	v_rcp_f32_e32 v13, v13
	v_rcp_f32_e32 v14, v14
	v_rcp_f32_e32 v15, v15
	v_rcp_f32_e32 v16, v16
	v_rcp_f32_e32 v17, v17
	v_rcp_f32_e32 v18, v18
	v_rcp_f32_e32 v19, v19
	v_rcp_f32_e32 v20, v20
	v_mul_f32_e32 v28, v28, v21
	v_mul_f32_e32 v29, v29, v22
	v_mul_f32_e32 v30, v30, v23
	v_mul_f32_e32 v31, v31, v24
	v_mul_f32_e32 v32, v32, v25
	v_mul_f32_e32 v33, v33, v26
	v_mul_f32_e32 v34, v34, v37
	v_mul_f32_e32 v35, v35, v43
	v_mul_f32_e32 v38, v38, v13
	v_mul_f32_e32 v39, v39, v14
	v_mul_f32_e32 v40, v40, v15
	v_mul_f32_e32 v41, v41, v16
	v_mul_f32_e32 v44, v44, v17
	v_mul_f32_e32 v45, v45, v18
	v_mul_f32_e32 v46, v46, v19
	v_mul_f32_e32 v47, v47, v20
	v_mul_f32_e32 v21, 0xbfb8aa3b, v54
	v_mul_f32_e32 v22, 0xbfb8aa3b, v55
	v_mul_f32_e32 v23, 0xbfb8aa3b, v56
	v_mul_f32_e32 v24, 0xbfb8aa3b, v57
	v_mul_f32_e32 v25, 0xbfb8aa3b, v62
	v_mul_f32_e32 v26, 0xbfb8aa3b, v63
	v_mul_f32_e32 v37, 0xbfb8aa3b, v64
	v_mul_f32_e32 v43, 0xbfb8aa3b, v65
	v_mul_f32_e32 v13, 0xbfb8aa3b, v78
	v_mul_f32_e32 v14, 0xbfb8aa3b, v79
	v_mul_f32_e32 v15, 0xbfb8aa3b, v80
	v_mul_f32_e32 v16, 0xbfb8aa3b, v81
	v_mul_f32_e32 v17, 0xbfb8aa3b, v88
	v_mul_f32_e32 v18, 0xbfb8aa3b, v89
	v_mul_f32_e32 v19, 0xbfb8aa3b, v90
	v_mul_f32_e32 v20, 0xbfb8aa3b, v91
	v_exp_f32_e32 v21, v21
	v_exp_f32_e32 v22, v22
	v_exp_f32_e32 v23, v23
	v_exp_f32_e32 v24, v24
	v_exp_f32_e32 v25, v25
	v_exp_f32_e32 v26, v26
	v_exp_f32_e32 v37, v37
	v_exp_f32_e32 v43, v43
	v_exp_f32_e32 v13, v13
	v_exp_f32_e32 v14, v14
	v_exp_f32_e32 v15, v15
	v_exp_f32_e32 v16, v16
	v_exp_f32_e32 v17, v17
	v_exp_f32_e32 v18, v18
	v_exp_f32_e32 v19, v19
	v_exp_f32_e32 v20, v20
	v_add_f32_e32 v21, 1.0, v21
	v_add_f32_e32 v22, 1.0, v22
	v_add_f32_e32 v23, 1.0, v23
	v_add_f32_e32 v24, 1.0, v24
	v_add_f32_e32 v25, 1.0, v25
	v_add_f32_e32 v26, 1.0, v26
	v_add_f32_e32 v37, 1.0, v37
	v_add_f32_e32 v43, 1.0, v43
	v_add_f32_e32 v13, 1.0, v13
	v_add_f32_e32 v14, 1.0, v14
	v_add_f32_e32 v15, 1.0, v15
	v_add_f32_e32 v16, 1.0, v16
	v_add_f32_e32 v17, 1.0, v17
	v_add_f32_e32 v18, 1.0, v18
	v_add_f32_e32 v19, 1.0, v19
	v_add_f32_e32 v20, 1.0, v20
	v_rcp_f32_e32 v21, v21
	v_rcp_f32_e32 v22, v22
	v_rcp_f32_e32 v23, v23
	v_rcp_f32_e32 v24, v24
	v_rcp_f32_e32 v25, v25
	v_rcp_f32_e32 v26, v26
	v_rcp_f32_e32 v37, v37
	v_rcp_f32_e32 v43, v43
	v_rcp_f32_e32 v13, v13
	v_rcp_f32_e32 v14, v14
	v_rcp_f32_e32 v15, v15
	v_rcp_f32_e32 v16, v16
	v_rcp_f32_e32 v17, v17
	v_rcp_f32_e32 v18, v18
	v_rcp_f32_e32 v19, v19
	v_rcp_f32_e32 v20, v20
	v_mul_f32_e32 v54, v54, v21
	v_mul_f32_e32 v55, v55, v22
	v_mul_f32_e32 v56, v56, v23
	v_mul_f32_e32 v57, v57, v24
	v_mul_f32_e32 v62, v62, v25
	v_mul_f32_e32 v63, v63, v26
	v_mul_f32_e32 v64, v64, v37
	v_mul_f32_e32 v65, v65, v43
	v_mul_f32_e32 v78, v78, v13
	v_mul_f32_e32 v79, v79, v14
	v_mul_f32_e32 v80, v80, v15
	v_mul_f32_e32 v81, v81, v16
	v_mul_f32_e32 v88, v88, v17
	v_mul_f32_e32 v89, v89, v18
	v_mul_f32_e32 v90, v90, v19
	v_mul_f32_e32 v91, v91, v20
	v_cvt_pk_bf16_f32 v28, v28, v29
	v_cvt_pk_bf16_f32 v29, v30, v31
	v_cvt_pk_bf16_f32 v32, v32, v33
	v_cvt_pk_bf16_f32 v33, v34, v35
	v_cvt_pk_bf16_f32 v38, v38, v39
	v_cvt_pk_bf16_f32 v39, v40, v41
	v_cvt_pk_bf16_f32 v44, v44, v45
	v_cvt_pk_bf16_f32 v45, v46, v47
	v_cvt_pk_bf16_f32 v54, v54, v55
	v_cvt_pk_bf16_f32 v55, v56, v57
	v_cvt_pk_bf16_f32 v62, v62, v63
	v_cvt_pk_bf16_f32 v63, v64, v65
	v_cvt_pk_bf16_f32 v78, v78, v79
	v_cvt_pk_bf16_f32 v79, v80, v81
	v_cvt_pk_bf16_f32 v88, v88, v89
	v_cvt_pk_bf16_f32 v89, v90, v91
	global_store_dwordx2 v[8:9], v[28:29], off
	v_lshl_add_u64 v[8:9], v[8:9], 0, s[8:9]
	global_store_dwordx2 v[8:9], v[32:33], off
	v_lshl_add_u64 v[8:9], v[8:9], 0, s[8:9]
	global_store_dwordx2 v[8:9], v[38:39], off
	v_lshl_add_u64 v[8:9], v[8:9], 0, s[8:9]
	global_store_dwordx2 v[8:9], v[44:45], off
	v_lshl_add_u64 v[8:9], v[8:9], 0, s[8:9]
	global_store_dwordx2 v[8:9], v[54:55], off
	v_lshl_add_u64 v[8:9], v[8:9], 0, s[8:9]
	global_store_dwordx2 v[8:9], v[62:63], off
	v_lshl_add_u64 v[8:9], v[8:9], 0, s[8:9]
	global_store_dwordx2 v[8:9], v[78:79], off
	v_lshl_add_u64 v[8:9], v[8:9], 0, s[8:9]
	global_store_dwordx2 v[8:9], v[88:89], off
	v_lshl_add_u64 v[8:9], v[8:9], 0, s[8:9]
	s_add_i32 s18, s18, s17
	s_cmp_lt_u32 s18, s16
	s_barrier
	s_cbranch_scc1 .LBB0_988
